# v40 + leading wave half (waves 0-3) waits for its DMA inside the MMA run instead of before the pre-MMA barrier
# baseline (speedup 1.0000x reference)
.LBB0_261:
	s_ashr_i32 s35, s34, 31
	s_lshl_b64 vcc, s[34:35], 21
	s_add_u32 s13, s30, vcc_lo
	s_addc_u32 s15, s31, vcc_hi
	s_add_u32 s54, s13, s54
	s_addc_u32 s55, s15, s55
	s_and_b64 s[86:87], s[86:87], exec
	s_cselect_b32 s13, s55, s11
	s_cselect_b32 s15, s54, s10
	s_add_i32 s35, s19, -2
	s_add_u32 s40, s10, 0x100
	s_addc_u32 s49, s11, 0
	s_add_u32 s10, s38, 0x100080
	s_addc_u32 s11, s39, 0
	s_mov_b32 s38, 0
	s_add_i32 vcc_lo, s38, 2
	s_add_u32 s39, s10, 0xfff00080
	s_addc_u32 s66, s11, -1
	s_add_i32 s67, 0, 0x10000
	s_cmp_eq_u32 s35, s38
	s_cselect_b32 s87, s53, s66
	s_cselect_b32 s86, s52, s39
	s_cselect_b32 s39, s13, s49
	s_cselect_b32 s38, s15, s40
	s_add_i32 vcc_hi, 0, 0x14000
	v_add_u32_e32 v142, s67, v1
	v_add_u32_e32 v180, vcc_hi, v1
	ds_read_b128 v[130:133], v142
	ds_read_b128 v[134:137], v142 offset:1024
	ds_read_b128 v[138:141], v142 offset:2048
	ds_read_b128 v[142:145], v142 offset:3072
	ds_read_b128 v[168:171], v180
	ds_read_b128 v[172:175], v180 offset:1024
	ds_read_b128 v[176:179], v180 offset:2048
	ds_read_b128 v[180:183], v180 offset:3072
	v_lshl_add_u64 v[184:185], s[10:11], 0, v[164:165]
	s_add_i32 m0, s85, 0xc000
	ds_read_b128 v[198:201], v197
	ds_read_b128 v[202:205], v197 offset:1024
	ds_read_b128 v[206:209], v197 offset:2048
	ds_read_b128 v[210:213], v197 offset:3072
	ds_read_b128 v[214:217], v197 offset:4096
	ds_read_b128 v[218:221], v197 offset:5120
	ds_read_b128 v[222:225], v197 offset:6144
	ds_read_b128 v[226:229], v197 offset:7168
	global_load_lds_dwordx4 v[184:185], off
	v_lshl_add_u64 v[184:185], s[10:11], 0, v[166:167]
	s_add_i32 m0, s85, 0xe000
	s_nop 0
	global_load_lds_dwordx4 v[184:185], off
	s_bitcmp1_b32 s97, 12
	s_cbranch_scc0 .Ldefer_1
	s_waitcnt vmcnt(8)
.Ldefer_1:
	s_waitcnt lgkmcnt(0)
	s_setprio 1
	s_barrier
	v_mfma_f32_16x16x32_bf16 v[114:117], v[130:133], v[198:201], 0
	v_mfma_f32_16x16x32_bf16 v[118:121], v[138:141], v[198:201], 0
	v_mfma_f32_16x16x32_bf16 v[102:105], v[130:133], v[206:209], 0
	v_mfma_f32_16x16x32_bf16 v[98:101], v[138:141], v[206:209], 0
	v_mfma_f32_16x16x32_bf16 v[86:89], v[130:133], v[214:217], 0
	v_mfma_f32_16x16x32_bf16 v[82:85], v[138:141], v[214:217], 0
	v_mfma_f32_16x16x32_bf16 v[54:57], v[130:133], v[222:225], 0
	v_mfma_f32_16x16x32_bf16 v[50:53], v[138:141], v[222:225], 0
	v_mfma_f32_16x16x32_bf16 v[114:117], v[134:137], v[202:205], v[114:117]
	v_mfma_f32_16x16x32_bf16 v[118:121], v[142:145], v[202:205], v[118:121]
	v_mfma_f32_16x16x32_bf16 v[102:105], v[134:137], v[210:213], v[102:105]
	v_mfma_f32_16x16x32_bf16 v[98:101], v[142:145], v[210:213], v[98:101]
	v_mfma_f32_16x16x32_bf16 v[86:89], v[134:137], v[218:221], v[86:89]
	v_mfma_f32_16x16x32_bf16 v[82:85], v[142:145], v[218:221], v[82:85]
	v_mfma_f32_16x16x32_bf16 v[54:57], v[134:137], v[226:229], v[54:57]
	v_mfma_f32_16x16x32_bf16 v[50:53], v[142:145], v[226:229], v[50:53]
	s_setprio 0
	s_setprio 1
	v_mfma_f32_16x16x32_bf16 v[126:129], v[168:171], v[198:201], 0
	v_mfma_f32_16x16x32_bf16 v[122:125], v[176:179], v[198:201], 0
	v_mfma_f32_16x16x32_bf16 v[110:113], v[168:171], v[206:209], 0
	v_mfma_f32_16x16x32_bf16 v[106:109], v[176:179], v[206:209], 0
	v_mfma_f32_16x16x32_bf16 v[94:97], v[168:171], v[214:217], 0
	v_mfma_f32_16x16x32_bf16 v[90:93], v[176:179], v[214:217], 0
	v_mfma_f32_16x16x32_bf16 v[70:73], v[168:171], v[222:225], 0
	v_mfma_f32_16x16x32_bf16 v[66:69], v[176:179], v[222:225], 0
	s_waitcnt vmcnt(8)
	v_mfma_f32_16x16x32_bf16 v[126:129], v[172:175], v[202:205], v[126:129]
	v_mfma_f32_16x16x32_bf16 v[122:125], v[180:183], v[202:205], v[122:125]
	v_mfma_f32_16x16x32_bf16 v[110:113], v[172:175], v[210:213], v[110:113]
	v_mfma_f32_16x16x32_bf16 v[106:109], v[180:183], v[210:213], v[106:109]
	v_mfma_f32_16x16x32_bf16 v[94:97], v[172:175], v[218:221], v[94:97]
	v_mfma_f32_16x16x32_bf16 v[90:93], v[180:183], v[218:221], v[90:93]
	v_mfma_f32_16x16x32_bf16 v[70:73], v[172:175], v[226:229], v[70:73]
	v_mfma_f32_16x16x32_bf16 v[66:69], v[180:183], v[226:229], v[66:69]
	s_barrier
	s_setprio 0
	s_add_i32 s66, s67, s97
	v_lshl_add_u64 v[184:185], s[38:39], 0, v[156:157]
	s_mov_b32 m0, s66
	ds_read_b128 v[198:201], v197 offset:16384
	ds_read_b128 v[202:205], v197 offset:17408
	ds_read_b128 v[206:209], v197 offset:18432
	ds_read_b128 v[210:213], v197 offset:19456
	ds_read_b128 v[214:217], v197 offset:20480
	ds_read_b128 v[218:221], v197 offset:21504
	ds_read_b128 v[222:225], v197 offset:22528
	ds_read_b128 v[226:229], v197 offset:23552
	global_load_lds_dwordx4 v[184:185], off
	s_add_i32 m0, s66, 0x2000
	s_add_u32 s66, s38, 0x100000
	v_lshl_add_u64 v[230:231], s[38:39], 0, v[160:161]
	s_addc_u32 s67, s39, 0
	s_add_i32 vcc_hi, vcc_hi, s97
	global_load_lds_dwordx4 v[230:231], off
	v_lshl_add_u64 v[232:233], s[66:67], 0, v[156:157]
	s_mov_b32 m0, vcc_hi
	v_lshl_add_u64 v[234:235], s[86:87], 0, v[158:159]
	global_load_lds_dwordx4 v[232:233], off
	v_lshl_add_u64 v[232:233], s[66:67], 0, v[160:161]
	s_add_i32 m0, vcc_hi, 0x2000
	s_nop 0
	global_load_lds_dwordx4 v[232:233], off
	v_lshl_add_u64 v[232:233], s[86:87], 0, v[154:155]
	s_mov_b32 m0, s85
	s_nop 0
	global_load_lds_dwordx4 v[232:233], off
	s_mov_b32 m0, s92
	s_nop 0
	global_load_lds_dwordx4 v[234:235], off
	s_bitcmp1_b32 s97, 12
	s_cbranch_scc0 .Ldefer_2
	s_waitcnt vmcnt(8)
.Ldefer_2:
	s_waitcnt lgkmcnt(0)
	s_setprio 1
	s_barrier
	v_mfma_f32_16x16x32_bf16 v[62:65], v[130:133], v[198:201], 0
	v_mfma_f32_16x16x32_bf16 v[58:61], v[138:141], v[198:201], 0
	v_mfma_f32_16x16x32_bf16 v[38:41], v[130:133], v[206:209], 0
	v_mfma_f32_16x16x32_bf16 v[34:37], v[138:141], v[206:209], 0
	v_mfma_f32_16x16x32_bf16 v[22:25], v[130:133], v[214:217], 0
	v_mfma_f32_16x16x32_bf16 v[18:21], v[138:141], v[214:217], 0
	v_mfma_f32_16x16x32_bf16 v[6:9], v[130:133], v[222:225], 0
	v_mfma_f32_16x16x32_bf16 v[2:5], v[138:141], v[222:225], 0
	v_mfma_f32_16x16x32_bf16 v[62:65], v[134:137], v[202:205], v[62:65]
	v_mfma_f32_16x16x32_bf16 v[58:61], v[142:145], v[202:205], v[58:61]
	v_mfma_f32_16x16x32_bf16 v[38:41], v[134:137], v[210:213], v[38:41]
	v_mfma_f32_16x16x32_bf16 v[34:37], v[142:145], v[210:213], v[34:37]
	v_mfma_f32_16x16x32_bf16 v[22:25], v[134:137], v[218:221], v[22:25]
	v_mfma_f32_16x16x32_bf16 v[18:21], v[142:145], v[218:221], v[18:21]
	v_mfma_f32_16x16x32_bf16 v[6:9], v[134:137], v[226:229], v[6:9]
	v_mfma_f32_16x16x32_bf16 v[2:5], v[142:145], v[226:229], v[2:5]
	s_setprio 0
	s_setprio 1
	v_mfma_f32_16x16x32_bf16 v[78:81], v[168:171], v[198:201], 0
	v_mfma_f32_16x16x32_bf16 v[74:77], v[176:179], v[198:201], 0
	v_mfma_f32_16x16x32_bf16 v[46:49], v[168:171], v[206:209], 0
	v_mfma_f32_16x16x32_bf16 v[42:45], v[176:179], v[206:209], 0
	v_mfma_f32_16x16x32_bf16 v[30:33], v[168:171], v[214:217], 0
	v_mfma_f32_16x16x32_bf16 v[26:29], v[176:179], v[214:217], 0
	v_mfma_f32_16x16x32_bf16 v[14:17], v[168:171], v[222:225], 0
	v_mfma_f32_16x16x32_bf16 v[10:13], v[176:179], v[222:225], 0
	s_waitcnt vmcnt(8)
	v_mfma_f32_16x16x32_bf16 v[78:81], v[172:175], v[202:205], v[78:81]
	v_mfma_f32_16x16x32_bf16 v[74:77], v[180:183], v[202:205], v[74:77]
	v_mfma_f32_16x16x32_bf16 v[46:49], v[172:175], v[210:213], v[46:49]
	v_mfma_f32_16x16x32_bf16 v[42:45], v[180:183], v[210:213], v[42:45]
	v_mfma_f32_16x16x32_bf16 v[30:33], v[172:175], v[218:221], v[30:33]
	v_mfma_f32_16x16x32_bf16 v[26:29], v[180:183], v[218:221], v[26:29]
	v_mfma_f32_16x16x32_bf16 v[14:17], v[172:175], v[226:229], v[14:17]
	v_mfma_f32_16x16x32_bf16 v[10:13], v[180:183], v[226:229], v[10:13]
	s_barrier
	s_setprio 0
	s_add_i32 vcc_hi, 0, 0x18000
	s_add_i32 s56, 0, 0x1c000
	v_add_u32_e32 v142, vcc_hi, v1
	v_add_u32_e32 v180, s56, v1
	ds_read_b128 v[130:133], v142
	ds_read_b128 v[134:137], v142 offset:1024
	ds_read_b128 v[138:141], v142 offset:2048
	ds_read_b128 v[142:145], v142 offset:3072
	ds_read_b128 v[168:171], v180
	ds_read_b128 v[172:175], v180 offset:1024
	ds_read_b128 v[176:179], v180 offset:2048
	ds_read_b128 v[180:183], v180 offset:3072
	s_add_u32 s66, s86, 0x100000
	s_addc_u32 s67, s87, 0
	s_mov_b32 m0, s93
	v_lshl_add_u64 v[236:237], s[66:67], 0, v[154:155]
	ds_read_b128 v[198:201], v197 offset:32768
	ds_read_b128 v[202:205], v197 offset:33792
	ds_read_b128 v[206:209], v197 offset:34816
	ds_read_b128 v[210:213], v197 offset:35840
	ds_read_b128 v[214:217], v197 offset:36864
	ds_read_b128 v[218:221], v197 offset:37888
	ds_read_b128 v[222:225], v197 offset:38912
	ds_read_b128 v[226:229], v197 offset:39936
	global_load_lds_dwordx4 v[236:237], off
	v_lshl_add_u64 v[236:237], s[66:67], 0, v[158:159]
	s_mov_b32 m0, s42
	s_nop 0
	global_load_lds_dwordx4 v[236:237], off
	s_bitcmp1_b32 s97, 12
	s_cbranch_scc0 .Ldefer_3
	s_waitcnt vmcnt(8)
.Ldefer_3:
	s_waitcnt lgkmcnt(0)
	s_setprio 1
	s_barrier
	v_mfma_f32_16x16x32_bf16 v[114:117], v[130:133], v[198:201], v[114:117]
	v_mfma_f32_16x16x32_bf16 v[118:121], v[138:141], v[198:201], v[118:121]
	v_mfma_f32_16x16x32_bf16 v[102:105], v[130:133], v[206:209], v[102:105]
	v_mfma_f32_16x16x32_bf16 v[98:101], v[138:141], v[206:209], v[98:101]
	v_mfma_f32_16x16x32_bf16 v[86:89], v[130:133], v[214:217], v[86:89]
	v_mfma_f32_16x16x32_bf16 v[82:85], v[138:141], v[214:217], v[82:85]
	v_mfma_f32_16x16x32_bf16 v[54:57], v[130:133], v[222:225], v[54:57]
	v_mfma_f32_16x16x32_bf16 v[50:53], v[138:141], v[222:225], v[50:53]
	v_mfma_f32_16x16x32_bf16 v[114:117], v[134:137], v[202:205], v[114:117]
	v_mfma_f32_16x16x32_bf16 v[118:121], v[142:145], v[202:205], v[118:121]
	v_mfma_f32_16x16x32_bf16 v[102:105], v[134:137], v[210:213], v[102:105]
	v_mfma_f32_16x16x32_bf16 v[98:101], v[142:145], v[210:213], v[98:101]
	v_mfma_f32_16x16x32_bf16 v[86:89], v[134:137], v[218:221], v[86:89]
	v_mfma_f32_16x16x32_bf16 v[82:85], v[142:145], v[218:221], v[82:85]
	v_mfma_f32_16x16x32_bf16 v[54:57], v[134:137], v[226:229], v[54:57]
	v_mfma_f32_16x16x32_bf16 v[50:53], v[142:145], v[226:229], v[50:53]
	s_setprio 0
	s_setprio 1
	v_mfma_f32_16x16x32_bf16 v[126:129], v[168:171], v[198:201], v[126:129]
	v_mfma_f32_16x16x32_bf16 v[122:125], v[176:179], v[198:201], v[122:125]
	v_mfma_f32_16x16x32_bf16 v[110:113], v[168:171], v[206:209], v[110:113]
	v_mfma_f32_16x16x32_bf16 v[106:109], v[176:179], v[206:209], v[106:109]
	v_mfma_f32_16x16x32_bf16 v[94:97], v[168:171], v[214:217], v[94:97]
	v_mfma_f32_16x16x32_bf16 v[90:93], v[176:179], v[214:217], v[90:93]
	v_mfma_f32_16x16x32_bf16 v[70:73], v[168:171], v[222:225], v[70:73]
	v_mfma_f32_16x16x32_bf16 v[66:69], v[176:179], v[222:225], v[66:69]
	s_waitcnt vmcnt(8)
	v_mfma_f32_16x16x32_bf16 v[126:129], v[172:175], v[202:205], v[126:129]
	v_mfma_f32_16x16x32_bf16 v[122:125], v[180:183], v[202:205], v[122:125]
	v_mfma_f32_16x16x32_bf16 v[110:113], v[172:175], v[210:213], v[110:113]
	v_mfma_f32_16x16x32_bf16 v[106:109], v[180:183], v[210:213], v[106:109]
	v_mfma_f32_16x16x32_bf16 v[94:97], v[172:175], v[218:221], v[94:97]
	v_mfma_f32_16x16x32_bf16 v[90:93], v[180:183], v[218:221], v[90:93]
	v_mfma_f32_16x16x32_bf16 v[70:73], v[172:175], v[226:229], v[70:73]
	v_mfma_f32_16x16x32_bf16 v[66:69], v[180:183], v[226:229], v[66:69]
	s_barrier
	s_setprio 0
	s_add_i32 s57, vcc_hi, s97
	v_lshl_add_u64 v[184:185], v[184:185], 0, s[94:95]
	s_mov_b32 m0, s57
	ds_read_b128 v[198:201], v197 offset:49152
	ds_read_b128 v[202:205], v197 offset:50176
	ds_read_b128 v[206:209], v197 offset:51200
	ds_read_b128 v[210:213], v197 offset:52224
	ds_read_b128 v[214:217], v197 offset:53248
	ds_read_b128 v[218:221], v197 offset:54272
	ds_read_b128 v[222:225], v197 offset:55296
	ds_read_b128 v[226:229], v197 offset:56320
	global_load_lds_dwordx4 v[184:185], off
	s_add_i32 m0, s57, 0x2000
	s_add_u32 s38, s38, 0x100080
	v_lshl_add_u64 v[184:185], v[230:231], 0, s[94:95]
	s_addc_u32 s39, s39, 0
	s_add_i32 s56, s56, s97
	global_load_lds_dwordx4 v[184:185], off
	v_lshl_add_u64 v[184:185], s[38:39], 0, v[156:157]
	s_mov_b32 m0, s56
	s_nop 0
	global_load_lds_dwordx4 v[184:185], off
	v_lshl_add_u64 v[184:185], s[38:39], 0, v[160:161]
	s_add_i32 m0, s56, 0x2000
	s_nop 0
	global_load_lds_dwordx4 v[184:185], off
	v_lshl_add_u64 v[184:185], v[232:233], 0, s[94:95]
	s_mov_b32 m0, s43
	s_nop 0
	global_load_lds_dwordx4 v[184:185], off
	v_lshl_add_u64 v[184:185], v[234:235], 0, s[94:95]
	s_mov_b32 m0, s90
	s_nop 0
	global_load_lds_dwordx4 v[184:185], off
	s_bitcmp1_b32 s97, 12
	s_cbranch_scc0 .Ldefer_4
	s_waitcnt vmcnt(8)
.Ldefer_4:
	s_waitcnt lgkmcnt(0)
	s_setprio 1
	s_barrier
	v_mfma_f32_16x16x32_bf16 v[62:65], v[130:133], v[198:201], v[62:65]
	v_mfma_f32_16x16x32_bf16 v[58:61], v[138:141], v[198:201], v[58:61]
	v_mfma_f32_16x16x32_bf16 v[38:41], v[130:133], v[206:209], v[38:41]
	v_mfma_f32_16x16x32_bf16 v[34:37], v[138:141], v[206:209], v[34:37]
	v_mfma_f32_16x16x32_bf16 v[22:25], v[130:133], v[214:217], v[22:25]
	v_mfma_f32_16x16x32_bf16 v[18:21], v[138:141], v[214:217], v[18:21]
	v_mfma_f32_16x16x32_bf16 v[6:9], v[130:133], v[222:225], v[6:9]
	v_mfma_f32_16x16x32_bf16 v[2:5], v[138:141], v[222:225], v[2:5]
	v_mfma_f32_16x16x32_bf16 v[62:65], v[134:137], v[202:205], v[62:65]
	v_mfma_f32_16x16x32_bf16 v[58:61], v[142:145], v[202:205], v[58:61]
	v_mfma_f32_16x16x32_bf16 v[38:41], v[134:137], v[210:213], v[38:41]
	v_mfma_f32_16x16x32_bf16 v[34:37], v[142:145], v[210:213], v[34:37]
	v_mfma_f32_16x16x32_bf16 v[22:25], v[134:137], v[218:221], v[22:25]
	v_mfma_f32_16x16x32_bf16 v[18:21], v[142:145], v[218:221], v[18:21]
	v_mfma_f32_16x16x32_bf16 v[6:9], v[134:137], v[226:229], v[6:9]
	v_mfma_f32_16x16x32_bf16 v[2:5], v[142:145], v[226:229], v[2:5]
	s_setprio 0
	s_setprio 1
	v_mfma_f32_16x16x32_bf16 v[78:81], v[168:171], v[198:201], v[78:81]
	v_mfma_f32_16x16x32_bf16 v[74:77], v[176:179], v[198:201], v[74:77]
	v_mfma_f32_16x16x32_bf16 v[46:49], v[168:171], v[206:209], v[46:49]
	v_mfma_f32_16x16x32_bf16 v[42:45], v[176:179], v[206:209], v[42:45]
	v_mfma_f32_16x16x32_bf16 v[30:33], v[168:171], v[214:217], v[30:33]
	v_mfma_f32_16x16x32_bf16 v[26:29], v[176:179], v[214:217], v[26:29]
	v_mfma_f32_16x16x32_bf16 v[14:17], v[168:171], v[222:225], v[14:17]
	v_mfma_f32_16x16x32_bf16 v[10:13], v[176:179], v[222:225], v[10:13]
	s_waitcnt vmcnt(8)
	v_mfma_f32_16x16x32_bf16 v[78:81], v[172:175], v[202:205], v[78:81]
	v_mfma_f32_16x16x32_bf16 v[74:77], v[180:183], v[202:205], v[74:77]
	v_mfma_f32_16x16x32_bf16 v[46:49], v[172:175], v[210:213], v[46:49]
	v_mfma_f32_16x16x32_bf16 v[42:45], v[180:183], v[210:213], v[42:45]
	v_mfma_f32_16x16x32_bf16 v[30:33], v[172:175], v[218:221], v[30:33]
	v_mfma_f32_16x16x32_bf16 v[26:29], v[180:183], v[218:221], v[26:29]
	v_mfma_f32_16x16x32_bf16 v[14:17], v[172:175], v[226:229], v[14:17]
	v_mfma_f32_16x16x32_bf16 v[10:13], v[180:183], v[226:229], v[10:13]
	s_barrier
	s_setprio 0
	s_add_u32 s40, s40, 0x100
	s_addc_u32 s49, s49, 0
	s_add_u32 s10, s10, 0x100
	s_addc_u32 s11, s11, 0
	s_cmp_ge_u32 vcc_lo, s19
	s_mov_b32 s38, vcc_lo
	s_cbranch_scc1 .Lpeel_done_0
.LBB0_262:
	s_add_i32 vcc_lo, s38, 2
	s_add_u32 s39, s10, 0xfff00080
	s_addc_u32 s66, s11, -1
	s_add_i32 s67, 0, 0x10000
	s_cmp_eq_u32 s35, s38
	s_cselect_b32 s87, s53, s66
	s_cselect_b32 s86, s52, s39
	s_cselect_b32 s39, s13, s49
	s_cselect_b32 s38, s15, s40
	s_add_i32 vcc_hi, 0, 0x14000
	v_add_u32_e32 v142, s67, v1
	v_add_u32_e32 v180, vcc_hi, v1
	ds_read_b128 v[130:133], v142
	ds_read_b128 v[134:137], v142 offset:1024
	ds_read_b128 v[138:141], v142 offset:2048
	ds_read_b128 v[142:145], v142 offset:3072
	ds_read_b128 v[168:171], v180
	ds_read_b128 v[172:175], v180 offset:1024
	ds_read_b128 v[176:179], v180 offset:2048
	ds_read_b128 v[180:183], v180 offset:3072
	v_lshl_add_u64 v[184:185], s[10:11], 0, v[164:165]
	s_add_i32 m0, s85, 0xc000
	ds_read_b128 v[198:201], v197
	ds_read_b128 v[202:205], v197 offset:1024
	ds_read_b128 v[206:209], v197 offset:2048
	ds_read_b128 v[210:213], v197 offset:3072
	ds_read_b128 v[214:217], v197 offset:4096
	ds_read_b128 v[218:221], v197 offset:5120
	ds_read_b128 v[222:225], v197 offset:6144
	ds_read_b128 v[226:229], v197 offset:7168
	global_load_lds_dwordx4 v[184:185], off
	v_lshl_add_u64 v[184:185], s[10:11], 0, v[166:167]
	s_add_i32 m0, s85, 0xe000
	s_nop 0
	global_load_lds_dwordx4 v[184:185], off
	s_bitcmp1_b32 s97, 12
	s_cbranch_scc0 .Ldefer_5
	s_waitcnt vmcnt(8)
.Ldefer_5:
	s_waitcnt lgkmcnt(0)
	s_setprio 1
	s_barrier
	v_mfma_f32_16x16x32_bf16 v[114:117], v[130:133], v[198:201], v[114:117]
	v_mfma_f32_16x16x32_bf16 v[118:121], v[138:141], v[198:201], v[118:121]
	v_mfma_f32_16x16x32_bf16 v[102:105], v[130:133], v[206:209], v[102:105]
	v_mfma_f32_16x16x32_bf16 v[98:101], v[138:141], v[206:209], v[98:101]
	v_mfma_f32_16x16x32_bf16 v[86:89], v[130:133], v[214:217], v[86:89]
	v_mfma_f32_16x16x32_bf16 v[82:85], v[138:141], v[214:217], v[82:85]
	v_mfma_f32_16x16x32_bf16 v[54:57], v[130:133], v[222:225], v[54:57]
	v_mfma_f32_16x16x32_bf16 v[50:53], v[138:141], v[222:225], v[50:53]
	v_mfma_f32_16x16x32_bf16 v[114:117], v[134:137], v[202:205], v[114:117]
	v_mfma_f32_16x16x32_bf16 v[118:121], v[142:145], v[202:205], v[118:121]
	v_mfma_f32_16x16x32_bf16 v[102:105], v[134:137], v[210:213], v[102:105]
	v_mfma_f32_16x16x32_bf16 v[98:101], v[142:145], v[210:213], v[98:101]
	v_mfma_f32_16x16x32_bf16 v[86:89], v[134:137], v[218:221], v[86:89]
	v_mfma_f32_16x16x32_bf16 v[82:85], v[142:145], v[218:221], v[82:85]
	v_mfma_f32_16x16x32_bf16 v[54:57], v[134:137], v[226:229], v[54:57]
	v_mfma_f32_16x16x32_bf16 v[50:53], v[142:145], v[226:229], v[50:53]
	s_setprio 0
	s_setprio 1
	v_mfma_f32_16x16x32_bf16 v[126:129], v[168:171], v[198:201], v[126:129]
	v_mfma_f32_16x16x32_bf16 v[122:125], v[176:179], v[198:201], v[122:125]
	v_mfma_f32_16x16x32_bf16 v[110:113], v[168:171], v[206:209], v[110:113]
	v_mfma_f32_16x16x32_bf16 v[106:109], v[176:179], v[206:209], v[106:109]
	v_mfma_f32_16x16x32_bf16 v[94:97], v[168:171], v[214:217], v[94:97]
	v_mfma_f32_16x16x32_bf16 v[90:93], v[176:179], v[214:217], v[90:93]
	v_mfma_f32_16x16x32_bf16 v[70:73], v[168:171], v[222:225], v[70:73]
	v_mfma_f32_16x16x32_bf16 v[66:69], v[176:179], v[222:225], v[66:69]
	s_waitcnt vmcnt(8)
	v_mfma_f32_16x16x32_bf16 v[126:129], v[172:175], v[202:205], v[126:129]
	v_mfma_f32_16x16x32_bf16 v[122:125], v[180:183], v[202:205], v[122:125]
	v_mfma_f32_16x16x32_bf16 v[110:113], v[172:175], v[210:213], v[110:113]
	v_mfma_f32_16x16x32_bf16 v[106:109], v[180:183], v[210:213], v[106:109]
	v_mfma_f32_16x16x32_bf16 v[94:97], v[172:175], v[218:221], v[94:97]
	v_mfma_f32_16x16x32_bf16 v[90:93], v[180:183], v[218:221], v[90:93]
	v_mfma_f32_16x16x32_bf16 v[70:73], v[172:175], v[226:229], v[70:73]
	v_mfma_f32_16x16x32_bf16 v[66:69], v[180:183], v[226:229], v[66:69]
	s_barrier
	s_setprio 0
	s_add_i32 s66, s67, s97
	v_lshl_add_u64 v[184:185], s[38:39], 0, v[156:157]
	s_mov_b32 m0, s66
	ds_read_b128 v[198:201], v197 offset:16384
	ds_read_b128 v[202:205], v197 offset:17408
	ds_read_b128 v[206:209], v197 offset:18432
	ds_read_b128 v[210:213], v197 offset:19456
	ds_read_b128 v[214:217], v197 offset:20480
	ds_read_b128 v[218:221], v197 offset:21504
	ds_read_b128 v[222:225], v197 offset:22528
	ds_read_b128 v[226:229], v197 offset:23552
	global_load_lds_dwordx4 v[184:185], off
	s_add_i32 m0, s66, 0x2000
	s_add_u32 s66, s38, 0x100000
	v_lshl_add_u64 v[230:231], s[38:39], 0, v[160:161]
	s_addc_u32 s67, s39, 0
	s_add_i32 vcc_hi, vcc_hi, s97
	global_load_lds_dwordx4 v[230:231], off
	v_lshl_add_u64 v[232:233], s[66:67], 0, v[156:157]
	s_mov_b32 m0, vcc_hi
	v_lshl_add_u64 v[234:235], s[86:87], 0, v[158:159]
	global_load_lds_dwordx4 v[232:233], off
	v_lshl_add_u64 v[232:233], s[66:67], 0, v[160:161]
	s_add_i32 m0, vcc_hi, 0x2000
	s_nop 0
	global_load_lds_dwordx4 v[232:233], off
	v_lshl_add_u64 v[232:233], s[86:87], 0, v[154:155]
	s_mov_b32 m0, s85
	s_nop 0
	global_load_lds_dwordx4 v[232:233], off
	s_mov_b32 m0, s92
	s_nop 0
	global_load_lds_dwordx4 v[234:235], off
	s_bitcmp1_b32 s97, 12
	s_cbranch_scc0 .Ldefer_6
	s_waitcnt vmcnt(8)
.Ldefer_6:
	s_waitcnt lgkmcnt(0)
	s_setprio 1
	s_barrier
	v_mfma_f32_16x16x32_bf16 v[62:65], v[130:133], v[198:201], v[62:65]
	v_mfma_f32_16x16x32_bf16 v[58:61], v[138:141], v[198:201], v[58:61]
	v_mfma_f32_16x16x32_bf16 v[38:41], v[130:133], v[206:209], v[38:41]
	v_mfma_f32_16x16x32_bf16 v[34:37], v[138:141], v[206:209], v[34:37]
	v_mfma_f32_16x16x32_bf16 v[22:25], v[130:133], v[214:217], v[22:25]
	v_mfma_f32_16x16x32_bf16 v[18:21], v[138:141], v[214:217], v[18:21]
	v_mfma_f32_16x16x32_bf16 v[6:9], v[130:133], v[222:225], v[6:9]
	v_mfma_f32_16x16x32_bf16 v[2:5], v[138:141], v[222:225], v[2:5]
	v_mfma_f32_16x16x32_bf16 v[62:65], v[134:137], v[202:205], v[62:65]
	v_mfma_f32_16x16x32_bf16 v[58:61], v[142:145], v[202:205], v[58:61]
	v_mfma_f32_16x16x32_bf16 v[38:41], v[134:137], v[210:213], v[38:41]
	v_mfma_f32_16x16x32_bf16 v[34:37], v[142:145], v[210:213], v[34:37]
	v_mfma_f32_16x16x32_bf16 v[22:25], v[134:137], v[218:221], v[22:25]
	v_mfma_f32_16x16x32_bf16 v[18:21], v[142:145], v[218:221], v[18:21]
	v_mfma_f32_16x16x32_bf16 v[6:9], v[134:137], v[226:229], v[6:9]
	v_mfma_f32_16x16x32_bf16 v[2:5], v[142:145], v[226:229], v[2:5]
	s_setprio 0
	s_setprio 1
	v_mfma_f32_16x16x32_bf16 v[78:81], v[168:171], v[198:201], v[78:81]
	v_mfma_f32_16x16x32_bf16 v[74:77], v[176:179], v[198:201], v[74:77]
	v_mfma_f32_16x16x32_bf16 v[46:49], v[168:171], v[206:209], v[46:49]
	v_mfma_f32_16x16x32_bf16 v[42:45], v[176:179], v[206:209], v[42:45]
	v_mfma_f32_16x16x32_bf16 v[30:33], v[168:171], v[214:217], v[30:33]
	v_mfma_f32_16x16x32_bf16 v[26:29], v[176:179], v[214:217], v[26:29]
	v_mfma_f32_16x16x32_bf16 v[14:17], v[168:171], v[222:225], v[14:17]
	v_mfma_f32_16x16x32_bf16 v[10:13], v[176:179], v[222:225], v[10:13]
	s_waitcnt vmcnt(8)
	v_mfma_f32_16x16x32_bf16 v[78:81], v[172:175], v[202:205], v[78:81]
	v_mfma_f32_16x16x32_bf16 v[74:77], v[180:183], v[202:205], v[74:77]
	v_mfma_f32_16x16x32_bf16 v[46:49], v[172:175], v[210:213], v[46:49]
	v_mfma_f32_16x16x32_bf16 v[42:45], v[180:183], v[210:213], v[42:45]
	v_mfma_f32_16x16x32_bf16 v[30:33], v[172:175], v[218:221], v[30:33]
	v_mfma_f32_16x16x32_bf16 v[26:29], v[180:183], v[218:221], v[26:29]
	v_mfma_f32_16x16x32_bf16 v[14:17], v[172:175], v[226:229], v[14:17]
	v_mfma_f32_16x16x32_bf16 v[10:13], v[180:183], v[226:229], v[10:13]
	s_barrier
	s_setprio 0
	s_add_i32 vcc_hi, 0, 0x18000
	s_add_i32 s56, 0, 0x1c000
	v_add_u32_e32 v142, vcc_hi, v1
	v_add_u32_e32 v180, s56, v1
	ds_read_b128 v[130:133], v142
	ds_read_b128 v[134:137], v142 offset:1024
	ds_read_b128 v[138:141], v142 offset:2048
	ds_read_b128 v[142:145], v142 offset:3072
	ds_read_b128 v[168:171], v180
	ds_read_b128 v[172:175], v180 offset:1024
	ds_read_b128 v[176:179], v180 offset:2048
	ds_read_b128 v[180:183], v180 offset:3072
	s_add_u32 s66, s86, 0x100000
	s_addc_u32 s67, s87, 0
	s_mov_b32 m0, s93
	v_lshl_add_u64 v[236:237], s[66:67], 0, v[154:155]
	ds_read_b128 v[198:201], v197 offset:32768
	ds_read_b128 v[202:205], v197 offset:33792
	ds_read_b128 v[206:209], v197 offset:34816
	ds_read_b128 v[210:213], v197 offset:35840
	ds_read_b128 v[214:217], v197 offset:36864
	ds_read_b128 v[218:221], v197 offset:37888
	ds_read_b128 v[222:225], v197 offset:38912
	ds_read_b128 v[226:229], v197 offset:39936
	global_load_lds_dwordx4 v[236:237], off
	v_lshl_add_u64 v[236:237], s[66:67], 0, v[158:159]
	s_mov_b32 m0, s42
	s_nop 0
	global_load_lds_dwordx4 v[236:237], off
	s_bitcmp1_b32 s97, 12
	s_cbranch_scc0 .Ldefer_7
	s_waitcnt vmcnt(8)

.Ldefer_8:
	s_waitcnt lgkmcnt(0)
	s_setprio 1
	s_barrier
	v_mfma_f32_16x16x32_bf16 v[62:65], v[130:133], v[198:201], v[62:65]
	v_mfma_f32_16x16x32_bf16 v[58:61], v[138:141], v[198:201], v[58:61]
	v_mfma_f32_16x16x32_bf16 v[38:41], v[130:133], v[206:209], v[38:41]
	v_mfma_f32_16x16x32_bf16 v[34:37], v[138:141], v[206:209], v[34:37]
	v_mfma_f32_16x16x32_bf16 v[22:25], v[130:133], v[214:217], v[22:25]
	v_mfma_f32_16x16x32_bf16 v[18:21], v[138:141], v[214:217], v[18:21]
	v_mfma_f32_16x16x32_bf16 v[6:9], v[130:133], v[222:225], v[6:9]
	v_mfma_f32_16x16x32_bf16 v[2:5], v[138:141], v[222:225], v[2:5]
	v_mfma_f32_16x16x32_bf16 v[62:65], v[134:137], v[202:205], v[62:65]
	v_mfma_f32_16x16x32_bf16 v[58:61], v[142:145], v[202:205], v[58:61]
	v_mfma_f32_16x16x32_bf16 v[38:41], v[134:137], v[210:213], v[38:41]
	v_mfma_f32_16x16x32_bf16 v[34:37], v[142:145], v[210:213], v[34:37]
	v_mfma_f32_16x16x32_bf16 v[22:25], v[134:137], v[218:221], v[22:25]
	v_mfma_f32_16x16x32_bf16 v[18:21], v[142:145], v[218:221], v[18:21]
	v_mfma_f32_16x16x32_bf16 v[6:9], v[134:137], v[226:229], v[6:9]
	v_mfma_f32_16x16x32_bf16 v[2:5], v[142:145], v[226:229], v[2:5]
	s_setprio 0
	s_setprio 1
	v_mfma_f32_16x16x32_bf16 v[78:81], v[168:171], v[198:201], v[78:81]
	v_mfma_f32_16x16x32_bf16 v[74:77], v[176:179], v[198:201], v[74:77]
	v_mfma_f32_16x16x32_bf16 v[46:49], v[168:171], v[206:209], v[46:49]
	v_mfma_f32_16x16x32_bf16 v[42:45], v[176:179], v[206:209], v[42:45]
	v_mfma_f32_16x16x32_bf16 v[30:33], v[168:171], v[214:217], v[30:33]
	v_mfma_f32_16x16x32_bf16 v[26:29], v[176:179], v[214:217], v[26:29]
	v_mfma_f32_16x16x32_bf16 v[14:17], v[168:171], v[222:225], v[14:17]
	v_mfma_f32_16x16x32_bf16 v[10:13], v[176:179], v[222:225], v[10:13]
	s_waitcnt vmcnt(8)
	v_mfma_f32_16x16x32_bf16 v[78:81], v[172:175], v[202:205], v[78:81]
	v_mfma_f32_16x16x32_bf16 v[74:77], v[180:183], v[202:205], v[74:77]
	v_mfma_f32_16x16x32_bf16 v[46:49], v[172:175], v[210:213], v[46:49]
	v_mfma_f32_16x16x32_bf16 v[42:45], v[180:183], v[210:213], v[42:45]
	v_mfma_f32_16x16x32_bf16 v[30:33], v[172:175], v[218:221], v[30:33]
	v_mfma_f32_16x16x32_bf16 v[26:29], v[180:183], v[218:221], v[26:29]
	v_mfma_f32_16x16x32_bf16 v[14:17], v[172:175], v[226:229], v[14:17]
	v_mfma_f32_16x16x32_bf16 v[10:13], v[180:183], v[226:229], v[10:13]
	s_barrier
	s_setprio 0
	s_add_u32 s40, s40, 0x100
	s_addc_u32 s49, s49, 0
	s_add_u32 s10, s10, 0x100
	s_addc_u32 s11, s11, 0
	s_cmp_ge_u32 vcc_lo, s19
	s_mov_b32 s38, vcc_lo
	s_cbranch_scc0 .LBB0_262

.LBB0_1692:
	s_ashr_i32 s13, s12, 31
	s_lshl_b64 s[16:17], s[12:13], 18
	s_add_u32 s16, s45, s16
	s_addc_u32 s17, s44, s17
	s_and_b64 s[26:27], s[26:27], exec
	s_cselect_b32 s13, s17, s25
	s_cselect_b32 s15, s16, s24
	s_add_u32 s34, s24, 0x100
	s_addc_u32 s35, s25, 0
	s_add_u32 s22, s22, 0x80080
	s_addc_u32 s23, s23, 0
	s_mov_b32 s36, -2
	ds_read_b128 v[128:131], v169
	ds_read_b128 v[132:135], v169 offset:1024
	ds_read_b128 v[136:139], v169 offset:2048
	ds_read_b128 v[140:143], v169 offset:3072
	ds_read_b128 v[158:161], v170
	ds_read_b128 v[162:165], v170 offset:1024
	ds_read_b128 v[172:175], v170 offset:2048
	ds_read_b128 v[176:179], v170 offset:3072
	s_add_u32 s24, s22, 0xfff80080
	s_addc_u32 s25, s23, -1
	s_cmp_eq_u32 s36, 4
	s_cselect_b32 s27, s5, s25
	s_cselect_b32 s26, s4, s24
	s_cselect_b32 s25, s13, s35
	s_cselect_b32 s24, s15, s34
	v_lshl_add_u64 v[212:213], s[22:23], 0, v[152:153]
	s_add_i32 m0, s94, 0xc000
	ds_read_b128 v[180:183], v171
	ds_read_b128 v[184:187], v171 offset:1024
	ds_read_b128 v[188:191], v171 offset:2048
	ds_read_b128 v[192:195], v171 offset:3072
	ds_read_b128 v[196:199], v171 offset:4096
	ds_read_b128 v[200:203], v171 offset:5120
	ds_read_b128 v[204:207], v171 offset:6144
	ds_read_b128 v[208:211], v171 offset:7168
	global_load_lds_dwordx4 v[212:213], off
	v_lshl_add_u64 v[212:213], s[22:23], 0, v[154:155]
	s_add_i32 m0, s94, 0xe000
	s_nop 0
	global_load_lds_dwordx4 v[212:213], off
	s_bitcmp1_b32 s97, 12
	s_cbranch_scc0 .Ldefer_9
	s_waitcnt vmcnt(8)
.Ldefer_9:
	s_waitcnt lgkmcnt(0)
	s_setprio 1
	s_barrier
	v_mfma_f32_16x16x32_bf16 v[80:83], v[128:131], v[180:183], 0
	v_mfma_f32_16x16x32_bf16 v[92:95], v[136:139], v[180:183], 0
	v_mfma_f32_16x16x32_bf16 v[84:87], v[128:131], v[188:191], 0
	v_mfma_f32_16x16x32_bf16 v[96:99], v[136:139], v[188:191], 0
	v_mfma_f32_16x16x32_bf16 v[88:91], v[128:131], v[196:199], 0
	v_mfma_f32_16x16x32_bf16 v[100:103], v[136:139], v[196:199], 0
	v_mfma_f32_16x16x32_bf16 v[72:75], v[128:131], v[204:207], 0
	v_mfma_f32_16x16x32_bf16 v[76:79], v[136:139], v[204:207], 0
	v_mfma_f32_16x16x32_bf16 v[80:83], v[132:135], v[184:187], v[80:83]
	v_mfma_f32_16x16x32_bf16 v[92:95], v[140:143], v[184:187], v[92:95]
	v_mfma_f32_16x16x32_bf16 v[84:87], v[132:135], v[192:195], v[84:87]
	v_mfma_f32_16x16x32_bf16 v[96:99], v[140:143], v[192:195], v[96:99]
	v_mfma_f32_16x16x32_bf16 v[88:91], v[132:135], v[200:203], v[88:91]
	v_mfma_f32_16x16x32_bf16 v[100:103], v[140:143], v[200:203], v[100:103]
	v_mfma_f32_16x16x32_bf16 v[72:75], v[132:135], v[208:211], v[72:75]
	v_mfma_f32_16x16x32_bf16 v[76:79], v[140:143], v[208:211], v[76:79]
	s_setprio 0
	s_setprio 1
	v_mfma_f32_16x16x32_bf16 v[104:107], v[158:161], v[180:183], 0
	v_mfma_f32_16x16x32_bf16 v[116:119], v[172:175], v[180:183], 0
	v_mfma_f32_16x16x32_bf16 v[108:111], v[158:161], v[188:191], 0
	v_mfma_f32_16x16x32_bf16 v[120:123], v[172:175], v[188:191], 0
	v_mfma_f32_16x16x32_bf16 v[112:115], v[158:161], v[196:199], 0
	v_mfma_f32_16x16x32_bf16 v[124:127], v[172:175], v[196:199], 0
	v_mfma_f32_16x16x32_bf16 v[68:71], v[158:161], v[204:207], 0
	v_mfma_f32_16x16x32_bf16 v[64:67], v[172:175], v[204:207], 0
	s_waitcnt vmcnt(8)
	v_mfma_f32_16x16x32_bf16 v[104:107], v[162:165], v[184:187], v[104:107]
	v_mfma_f32_16x16x32_bf16 v[116:119], v[176:179], v[184:187], v[116:119]
	v_mfma_f32_16x16x32_bf16 v[108:111], v[162:165], v[192:195], v[108:111]
	v_mfma_f32_16x16x32_bf16 v[120:123], v[176:179], v[192:195], v[120:123]
	v_mfma_f32_16x16x32_bf16 v[112:115], v[162:165], v[200:203], v[112:115]
	v_mfma_f32_16x16x32_bf16 v[124:127], v[176:179], v[200:203], v[124:127]
	v_mfma_f32_16x16x32_bf16 v[68:71], v[162:165], v[208:211], v[68:71]
	v_mfma_f32_16x16x32_bf16 v[64:67], v[176:179], v[208:211], v[64:67]
	s_barrier
	s_setprio 0
	s_add_i32 s37, s31, s97
	v_lshl_add_u64 v[212:213], s[24:25], 0, v[148:149]
	s_mov_b32 m0, s37
	ds_read_b128 v[180:183], v171 offset:16384
	ds_read_b128 v[184:187], v171 offset:17408
	ds_read_b128 v[188:191], v171 offset:18432
	ds_read_b128 v[192:195], v171 offset:19456
	ds_read_b128 v[196:199], v171 offset:20480
	ds_read_b128 v[200:203], v171 offset:21504
	ds_read_b128 v[204:207], v171 offset:22528
	ds_read_b128 v[208:211], v171 offset:23552
	global_load_lds_dwordx4 v[212:213], off
	s_add_i32 m0, s37, 0x2000
	s_add_u32 s38, s24, 0x20000
	v_lshl_add_u64 v[214:215], s[24:25], 0, v[144:145]
	s_addc_u32 s39, s25, 0
	s_add_i32 s37, s33, s97
	global_load_lds_dwordx4 v[214:215], off
	v_lshl_add_u64 v[216:217], s[38:39], 0, v[148:149]
	s_mov_b32 m0, s37
	v_lshl_add_u64 v[218:219], s[26:27], 0, v[146:147]
	global_load_lds_dwordx4 v[216:217], off
	v_lshl_add_u64 v[216:217], s[38:39], 0, v[144:145]
	s_add_i32 m0, s37, 0x2000
	s_nop 0
	global_load_lds_dwordx4 v[216:217], off
	v_lshl_add_u64 v[216:217], s[26:27], 0, v[150:151]
	s_mov_b32 m0, s94
	s_nop 0
	global_load_lds_dwordx4 v[216:217], off
	s_mov_b32 m0, s3
	s_nop 0
	global_load_lds_dwordx4 v[218:219], off
	s_bitcmp1_b32 s97, 12
	s_cbranch_scc0 .Ldefer_10
	s_waitcnt vmcnt(8)
.Ldefer_10:
	s_waitcnt lgkmcnt(0)
	s_setprio 1
	s_barrier
	v_mfma_f32_16x16x32_bf16 v[48:51], v[128:131], v[180:183], 0
	v_mfma_f32_16x16x32_bf16 v[52:55], v[136:139], v[180:183], 0
	v_mfma_f32_16x16x32_bf16 v[32:35], v[128:131], v[188:191], 0
	v_mfma_f32_16x16x32_bf16 v[36:39], v[136:139], v[188:191], 0
	v_mfma_f32_16x16x32_bf16 v[16:19], v[128:131], v[196:199], 0
	v_mfma_f32_16x16x32_bf16 v[20:23], v[136:139], v[196:199], 0
	v_mfma_f32_16x16x32_bf16 v[0:3], v[128:131], v[204:207], 0
	v_mfma_f32_16x16x32_bf16 v[4:7], v[136:139], v[204:207], 0
	v_mfma_f32_16x16x32_bf16 v[48:51], v[132:135], v[184:187], v[48:51]
	v_mfma_f32_16x16x32_bf16 v[52:55], v[140:143], v[184:187], v[52:55]
	v_mfma_f32_16x16x32_bf16 v[32:35], v[132:135], v[192:195], v[32:35]
	v_mfma_f32_16x16x32_bf16 v[36:39], v[140:143], v[192:195], v[36:39]
	v_mfma_f32_16x16x32_bf16 v[16:19], v[132:135], v[200:203], v[16:19]
	v_mfma_f32_16x16x32_bf16 v[20:23], v[140:143], v[200:203], v[20:23]
	v_mfma_f32_16x16x32_bf16 v[0:3], v[132:135], v[208:211], v[0:3]
	v_mfma_f32_16x16x32_bf16 v[4:7], v[140:143], v[208:211], v[4:7]
	s_setprio 0
	s_setprio 1
	v_mfma_f32_16x16x32_bf16 v[56:59], v[158:161], v[180:183], 0
	v_mfma_f32_16x16x32_bf16 v[60:63], v[172:175], v[180:183], 0
	v_mfma_f32_16x16x32_bf16 v[40:43], v[158:161], v[188:191], 0
	v_mfma_f32_16x16x32_bf16 v[44:47], v[172:175], v[188:191], 0
	v_mfma_f32_16x16x32_bf16 v[24:27], v[158:161], v[196:199], 0
	v_mfma_f32_16x16x32_bf16 v[28:31], v[172:175], v[196:199], 0
	v_mfma_f32_16x16x32_bf16 v[8:11], v[158:161], v[204:207], 0
	v_mfma_f32_16x16x32_bf16 v[12:15], v[172:175], v[204:207], 0
	s_waitcnt vmcnt(8)
	v_mfma_f32_16x16x32_bf16 v[56:59], v[162:165], v[184:187], v[56:59]
	v_mfma_f32_16x16x32_bf16 v[60:63], v[176:179], v[184:187], v[60:63]
	v_mfma_f32_16x16x32_bf16 v[40:43], v[162:165], v[192:195], v[40:43]
	v_mfma_f32_16x16x32_bf16 v[44:47], v[176:179], v[192:195], v[44:47]
	v_mfma_f32_16x16x32_bf16 v[24:27], v[162:165], v[200:203], v[24:27]
	v_mfma_f32_16x16x32_bf16 v[28:31], v[176:179], v[200:203], v[28:31]
	v_mfma_f32_16x16x32_bf16 v[8:11], v[162:165], v[208:211], v[8:11]
	v_mfma_f32_16x16x32_bf16 v[12:15], v[176:179], v[208:211], v[12:15]
	s_barrier
	s_setprio 0
	s_add_i32 s37, 0, 0x18000
	s_add_i32 s38, 0, 0x1c000
	v_add_u32_e32 v140, s37, v167
	v_add_u32_e32 v176, s38, v167
	ds_read_b128 v[128:131], v140
	ds_read_b128 v[132:135], v140 offset:1024
	ds_read_b128 v[136:139], v140 offset:2048
	ds_read_b128 v[140:143], v140 offset:3072
	ds_read_b128 v[158:161], v176
	ds_read_b128 v[162:165], v176 offset:1024
	ds_read_b128 v[172:175], v176 offset:2048
	ds_read_b128 v[176:179], v176 offset:3072
	s_add_u32 s26, s26, 0x80000
	s_addc_u32 s27, s27, 0
	s_mov_b32 m0, s7
	v_lshl_add_u64 v[220:221], s[26:27], 0, v[150:151]
	ds_read_b128 v[180:183], v171 offset:32768
	ds_read_b128 v[184:187], v171 offset:33792
	ds_read_b128 v[188:191], v171 offset:34816
	ds_read_b128 v[192:195], v171 offset:35840
	ds_read_b128 v[196:199], v171 offset:36864
	ds_read_b128 v[200:203], v171 offset:37888
	ds_read_b128 v[204:207], v171 offset:38912
	ds_read_b128 v[208:211], v171 offset:39936
	global_load_lds_dwordx4 v[220:221], off
	v_lshl_add_u64 v[220:221], s[26:27], 0, v[146:147]
	s_mov_b32 m0, s19
	s_nop 0
	global_load_lds_dwordx4 v[220:221], off
	s_bitcmp1_b32 s97, 12
	s_cbranch_scc0 .Ldefer_11
	s_waitcnt vmcnt(8)
.Ldefer_11:
	s_waitcnt lgkmcnt(0)
	s_setprio 1
	s_barrier
	v_mfma_f32_16x16x32_bf16 v[80:83], v[128:131], v[180:183], v[80:83]
	v_mfma_f32_16x16x32_bf16 v[92:95], v[136:139], v[180:183], v[92:95]
	v_mfma_f32_16x16x32_bf16 v[84:87], v[128:131], v[188:191], v[84:87]
	v_mfma_f32_16x16x32_bf16 v[96:99], v[136:139], v[188:191], v[96:99]
	v_mfma_f32_16x16x32_bf16 v[88:91], v[128:131], v[196:199], v[88:91]
	v_mfma_f32_16x16x32_bf16 v[100:103], v[136:139], v[196:199], v[100:103]
	v_mfma_f32_16x16x32_bf16 v[72:75], v[128:131], v[204:207], v[72:75]
	v_mfma_f32_16x16x32_bf16 v[76:79], v[136:139], v[204:207], v[76:79]
	v_mfma_f32_16x16x32_bf16 v[80:83], v[132:135], v[184:187], v[80:83]
	v_mfma_f32_16x16x32_bf16 v[92:95], v[140:143], v[184:187], v[92:95]
	v_mfma_f32_16x16x32_bf16 v[84:87], v[132:135], v[192:195], v[84:87]
	v_mfma_f32_16x16x32_bf16 v[96:99], v[140:143], v[192:195], v[96:99]
	v_mfma_f32_16x16x32_bf16 v[88:91], v[132:135], v[200:203], v[88:91]
	v_mfma_f32_16x16x32_bf16 v[100:103], v[140:143], v[200:203], v[100:103]
	v_mfma_f32_16x16x32_bf16 v[72:75], v[132:135], v[208:211], v[72:75]
	v_mfma_f32_16x16x32_bf16 v[76:79], v[140:143], v[208:211], v[76:79]
	s_setprio 0
	s_setprio 1
	v_mfma_f32_16x16x32_bf16 v[104:107], v[158:161], v[180:183], v[104:107]
	v_mfma_f32_16x16x32_bf16 v[116:119], v[172:175], v[180:183], v[116:119]
	v_mfma_f32_16x16x32_bf16 v[108:111], v[158:161], v[188:191], v[108:111]
	v_mfma_f32_16x16x32_bf16 v[120:123], v[172:175], v[188:191], v[120:123]
	v_mfma_f32_16x16x32_bf16 v[112:115], v[158:161], v[196:199], v[112:115]
	v_mfma_f32_16x16x32_bf16 v[124:127], v[172:175], v[196:199], v[124:127]
	v_mfma_f32_16x16x32_bf16 v[68:71], v[158:161], v[204:207], v[68:71]
	v_mfma_f32_16x16x32_bf16 v[64:67], v[172:175], v[204:207], v[64:67]
	s_waitcnt vmcnt(8)
	v_mfma_f32_16x16x32_bf16 v[104:107], v[162:165], v[184:187], v[104:107]
	v_mfma_f32_16x16x32_bf16 v[116:119], v[176:179], v[184:187], v[116:119]
	v_mfma_f32_16x16x32_bf16 v[108:111], v[162:165], v[192:195], v[108:111]
	v_mfma_f32_16x16x32_bf16 v[120:123], v[176:179], v[192:195], v[120:123]
	v_mfma_f32_16x16x32_bf16 v[112:115], v[162:165], v[200:203], v[112:115]
	v_mfma_f32_16x16x32_bf16 v[124:127], v[176:179], v[200:203], v[124:127]
	v_mfma_f32_16x16x32_bf16 v[68:71], v[162:165], v[208:211], v[68:71]
	v_mfma_f32_16x16x32_bf16 v[64:67], v[176:179], v[208:211], v[64:67]
	s_barrier
	s_setprio 0
	s_add_i32 s26, s37, s97
	v_lshl_add_u64 v[212:213], v[212:213], 0, s[0:1]
	s_mov_b32 m0, s26
	ds_read_b128 v[180:183], v171 offset:49152
	ds_read_b128 v[184:187], v171 offset:50176
	ds_read_b128 v[188:191], v171 offset:51200
	ds_read_b128 v[192:195], v171 offset:52224
	ds_read_b128 v[196:199], v171 offset:53248
	ds_read_b128 v[200:203], v171 offset:54272
	ds_read_b128 v[204:207], v171 offset:55296
	ds_read_b128 v[208:211], v171 offset:56320
	global_load_lds_dwordx4 v[212:213], off
	s_add_i32 m0, s26, 0x2000
	s_add_u32 s24, s24, 0x20080
	v_lshl_add_u64 v[212:213], v[214:215], 0, s[0:1]
	s_addc_u32 s25, s25, 0
	s_add_i32 s26, s38, s97
	global_load_lds_dwordx4 v[212:213], off
	v_lshl_add_u64 v[212:213], s[24:25], 0, v[148:149]
	s_mov_b32 m0, s26
	s_nop 0
	global_load_lds_dwordx4 v[212:213], off
	v_lshl_add_u64 v[212:213], s[24:25], 0, v[144:145]
	s_add_i32 m0, s26, 0x2000
	s_nop 0
	global_load_lds_dwordx4 v[212:213], off
	v_lshl_add_u64 v[212:213], v[216:217], 0, s[0:1]
	s_mov_b32 m0, s28
	s_nop 0
	global_load_lds_dwordx4 v[212:213], off
	v_lshl_add_u64 v[212:213], v[218:219], 0, s[0:1]
	s_mov_b32 m0, s29
	s_nop 0
	global_load_lds_dwordx4 v[212:213], off
	s_bitcmp1_b32 s97, 12
	s_cbranch_scc0 .Ldefer_12
	s_waitcnt vmcnt(8)
.Ldefer_12:
	s_waitcnt lgkmcnt(0)
	s_setprio 1
	s_barrier
	v_mfma_f32_16x16x32_bf16 v[48:51], v[128:131], v[180:183], v[48:51]
	v_mfma_f32_16x16x32_bf16 v[52:55], v[136:139], v[180:183], v[52:55]
	v_mfma_f32_16x16x32_bf16 v[32:35], v[128:131], v[188:191], v[32:35]
	v_mfma_f32_16x16x32_bf16 v[36:39], v[136:139], v[188:191], v[36:39]
	v_mfma_f32_16x16x32_bf16 v[16:19], v[128:131], v[196:199], v[16:19]
	v_mfma_f32_16x16x32_bf16 v[20:23], v[136:139], v[196:199], v[20:23]
	v_mfma_f32_16x16x32_bf16 v[0:3], v[128:131], v[204:207], v[0:3]
	v_mfma_f32_16x16x32_bf16 v[4:7], v[136:139], v[204:207], v[4:7]
	v_mfma_f32_16x16x32_bf16 v[48:51], v[132:135], v[184:187], v[48:51]
	v_mfma_f32_16x16x32_bf16 v[52:55], v[140:143], v[184:187], v[52:55]
	v_mfma_f32_16x16x32_bf16 v[32:35], v[132:135], v[192:195], v[32:35]
	v_mfma_f32_16x16x32_bf16 v[36:39], v[140:143], v[192:195], v[36:39]
	v_mfma_f32_16x16x32_bf16 v[16:19], v[132:135], v[200:203], v[16:19]
	v_mfma_f32_16x16x32_bf16 v[20:23], v[140:143], v[200:203], v[20:23]
	v_mfma_f32_16x16x32_bf16 v[0:3], v[132:135], v[208:211], v[0:3]
	v_mfma_f32_16x16x32_bf16 v[4:7], v[140:143], v[208:211], v[4:7]
	s_setprio 0
	s_setprio 1
	v_mfma_f32_16x16x32_bf16 v[56:59], v[158:161], v[180:183], v[56:59]
	v_mfma_f32_16x16x32_bf16 v[60:63], v[172:175], v[180:183], v[60:63]
	v_mfma_f32_16x16x32_bf16 v[40:43], v[158:161], v[188:191], v[40:43]
	v_mfma_f32_16x16x32_bf16 v[44:47], v[172:175], v[188:191], v[44:47]
	v_mfma_f32_16x16x32_bf16 v[24:27], v[158:161], v[196:199], v[24:27]
	v_mfma_f32_16x16x32_bf16 v[28:31], v[172:175], v[196:199], v[28:31]
	v_mfma_f32_16x16x32_bf16 v[8:11], v[158:161], v[204:207], v[8:11]
	v_mfma_f32_16x16x32_bf16 v[12:15], v[172:175], v[204:207], v[12:15]
	s_waitcnt vmcnt(8)
	v_mfma_f32_16x16x32_bf16 v[56:59], v[162:165], v[184:187], v[56:59]
	v_mfma_f32_16x16x32_bf16 v[60:63], v[176:179], v[184:187], v[60:63]
	v_mfma_f32_16x16x32_bf16 v[40:43], v[162:165], v[192:195], v[40:43]
	v_mfma_f32_16x16x32_bf16 v[44:47], v[176:179], v[192:195], v[44:47]
	v_mfma_f32_16x16x32_bf16 v[24:27], v[162:165], v[200:203], v[24:27]
	v_mfma_f32_16x16x32_bf16 v[28:31], v[176:179], v[200:203], v[28:31]
	v_mfma_f32_16x16x32_bf16 v[8:11], v[162:165], v[208:211], v[8:11]
	v_mfma_f32_16x16x32_bf16 v[12:15], v[176:179], v[208:211], v[12:15]
	s_barrier
	s_setprio 0
	s_add_i32 s36, s36, 2
	s_add_u32 s34, s34, 0x100
	s_addc_u32 s35, s35, 0
	s_add_u32 s22, s22, 0x100
	s_addc_u32 s23, s23, 0
	s_cmp_gt_u32 s36, 5
	s_cbranch_scc1 .Lpeel_done_1
.LBB0_1693:
	ds_read_b128 v[128:131], v169
	ds_read_b128 v[132:135], v169 offset:1024
	ds_read_b128 v[136:139], v169 offset:2048
	ds_read_b128 v[140:143], v169 offset:3072
	ds_read_b128 v[158:161], v170
	ds_read_b128 v[162:165], v170 offset:1024
	ds_read_b128 v[172:175], v170 offset:2048
	ds_read_b128 v[176:179], v170 offset:3072
	s_add_u32 s24, s22, 0xfff80080
	s_addc_u32 s25, s23, -1
	s_cmp_eq_u32 s36, 4
	s_cselect_b32 s27, s5, s25
	s_cselect_b32 s26, s4, s24
	s_cselect_b32 s25, s13, s35
	s_cselect_b32 s24, s15, s34
	v_lshl_add_u64 v[212:213], s[22:23], 0, v[152:153]
	s_add_i32 m0, s94, 0xc000
	ds_read_b128 v[180:183], v171
	ds_read_b128 v[184:187], v171 offset:1024
	ds_read_b128 v[188:191], v171 offset:2048
	ds_read_b128 v[192:195], v171 offset:3072
	ds_read_b128 v[196:199], v171 offset:4096
	ds_read_b128 v[200:203], v171 offset:5120
	ds_read_b128 v[204:207], v171 offset:6144
	ds_read_b128 v[208:211], v171 offset:7168
	global_load_lds_dwordx4 v[212:213], off
	v_lshl_add_u64 v[212:213], s[22:23], 0, v[154:155]
	s_add_i32 m0, s94, 0xe000
	s_nop 0
	global_load_lds_dwordx4 v[212:213], off
	s_bitcmp1_b32 s97, 12
	s_cbranch_scc0 .Ldefer_13
	s_waitcnt vmcnt(8)
.Ldefer_13:
	s_waitcnt lgkmcnt(0)
	s_setprio 1
	s_barrier
	v_mfma_f32_16x16x32_bf16 v[80:83], v[128:131], v[180:183], v[80:83]
	v_mfma_f32_16x16x32_bf16 v[92:95], v[136:139], v[180:183], v[92:95]
	v_mfma_f32_16x16x32_bf16 v[84:87], v[128:131], v[188:191], v[84:87]
	v_mfma_f32_16x16x32_bf16 v[96:99], v[136:139], v[188:191], v[96:99]
	v_mfma_f32_16x16x32_bf16 v[88:91], v[128:131], v[196:199], v[88:91]
	v_mfma_f32_16x16x32_bf16 v[100:103], v[136:139], v[196:199], v[100:103]
	v_mfma_f32_16x16x32_bf16 v[72:75], v[128:131], v[204:207], v[72:75]
	v_mfma_f32_16x16x32_bf16 v[76:79], v[136:139], v[204:207], v[76:79]
	v_mfma_f32_16x16x32_bf16 v[80:83], v[132:135], v[184:187], v[80:83]
	v_mfma_f32_16x16x32_bf16 v[92:95], v[140:143], v[184:187], v[92:95]
	v_mfma_f32_16x16x32_bf16 v[84:87], v[132:135], v[192:195], v[84:87]
	v_mfma_f32_16x16x32_bf16 v[96:99], v[140:143], v[192:195], v[96:99]
	v_mfma_f32_16x16x32_bf16 v[88:91], v[132:135], v[200:203], v[88:91]
	v_mfma_f32_16x16x32_bf16 v[100:103], v[140:143], v[200:203], v[100:103]
	v_mfma_f32_16x16x32_bf16 v[72:75], v[132:135], v[208:211], v[72:75]
	v_mfma_f32_16x16x32_bf16 v[76:79], v[140:143], v[208:211], v[76:79]
	s_setprio 0
	s_setprio 1
	v_mfma_f32_16x16x32_bf16 v[104:107], v[158:161], v[180:183], v[104:107]
	v_mfma_f32_16x16x32_bf16 v[116:119], v[172:175], v[180:183], v[116:119]
	v_mfma_f32_16x16x32_bf16 v[108:111], v[158:161], v[188:191], v[108:111]
	v_mfma_f32_16x16x32_bf16 v[120:123], v[172:175], v[188:191], v[120:123]
	v_mfma_f32_16x16x32_bf16 v[112:115], v[158:161], v[196:199], v[112:115]
	v_mfma_f32_16x16x32_bf16 v[124:127], v[172:175], v[196:199], v[124:127]
	v_mfma_f32_16x16x32_bf16 v[68:71], v[158:161], v[204:207], v[68:71]
	v_mfma_f32_16x16x32_bf16 v[64:67], v[172:175], v[204:207], v[64:67]
	s_waitcnt vmcnt(8)
	v_mfma_f32_16x16x32_bf16 v[104:107], v[162:165], v[184:187], v[104:107]
	v_mfma_f32_16x16x32_bf16 v[116:119], v[176:179], v[184:187], v[116:119]
	v_mfma_f32_16x16x32_bf16 v[108:111], v[162:165], v[192:195], v[108:111]
	v_mfma_f32_16x16x32_bf16 v[120:123], v[176:179], v[192:195], v[120:123]
	v_mfma_f32_16x16x32_bf16 v[112:115], v[162:165], v[200:203], v[112:115]
	v_mfma_f32_16x16x32_bf16 v[124:127], v[176:179], v[200:203], v[124:127]
	v_mfma_f32_16x16x32_bf16 v[68:71], v[162:165], v[208:211], v[68:71]
	v_mfma_f32_16x16x32_bf16 v[64:67], v[176:179], v[208:211], v[64:67]
	s_barrier
	s_setprio 0
	s_add_i32 s37, s31, s97
	v_lshl_add_u64 v[212:213], s[24:25], 0, v[148:149]
	s_mov_b32 m0, s37
	ds_read_b128 v[180:183], v171 offset:16384
	ds_read_b128 v[184:187], v171 offset:17408
	ds_read_b128 v[188:191], v171 offset:18432
	ds_read_b128 v[192:195], v171 offset:19456
	ds_read_b128 v[196:199], v171 offset:20480
	ds_read_b128 v[200:203], v171 offset:21504
	ds_read_b128 v[204:207], v171 offset:22528
	ds_read_b128 v[208:211], v171 offset:23552
	global_load_lds_dwordx4 v[212:213], off
	s_add_i32 m0, s37, 0x2000
	s_add_u32 s38, s24, 0x20000
	v_lshl_add_u64 v[214:215], s[24:25], 0, v[144:145]
	s_addc_u32 s39, s25, 0
	s_add_i32 s37, s33, s97
	global_load_lds_dwordx4 v[214:215], off
	v_lshl_add_u64 v[216:217], s[38:39], 0, v[148:149]
	s_mov_b32 m0, s37
	v_lshl_add_u64 v[218:219], s[26:27], 0, v[146:147]
	global_load_lds_dwordx4 v[216:217], off
	v_lshl_add_u64 v[216:217], s[38:39], 0, v[144:145]
	s_add_i32 m0, s37, 0x2000
	s_nop 0
	global_load_lds_dwordx4 v[216:217], off
	v_lshl_add_u64 v[216:217], s[26:27], 0, v[150:151]
	s_mov_b32 m0, s94
	s_nop 0
	global_load_lds_dwordx4 v[216:217], off
	s_mov_b32 m0, s3
	s_nop 0
	global_load_lds_dwordx4 v[218:219], off
	s_bitcmp1_b32 s97, 12
	s_cbranch_scc0 .Ldefer_14
	s_waitcnt vmcnt(8)
.Ldefer_14:
	s_waitcnt lgkmcnt(0)
	s_setprio 1
	s_barrier
	v_mfma_f32_16x16x32_bf16 v[48:51], v[128:131], v[180:183], v[48:51]
	v_mfma_f32_16x16x32_bf16 v[52:55], v[136:139], v[180:183], v[52:55]
	v_mfma_f32_16x16x32_bf16 v[32:35], v[128:131], v[188:191], v[32:35]
	v_mfma_f32_16x16x32_bf16 v[36:39], v[136:139], v[188:191], v[36:39]
	v_mfma_f32_16x16x32_bf16 v[16:19], v[128:131], v[196:199], v[16:19]
	v_mfma_f32_16x16x32_bf16 v[20:23], v[136:139], v[196:199], v[20:23]
	v_mfma_f32_16x16x32_bf16 v[0:3], v[128:131], v[204:207], v[0:3]
	v_mfma_f32_16x16x32_bf16 v[4:7], v[136:139], v[204:207], v[4:7]
	v_mfma_f32_16x16x32_bf16 v[48:51], v[132:135], v[184:187], v[48:51]
	v_mfma_f32_16x16x32_bf16 v[52:55], v[140:143], v[184:187], v[52:55]
	v_mfma_f32_16x16x32_bf16 v[32:35], v[132:135], v[192:195], v[32:35]
	v_mfma_f32_16x16x32_bf16 v[36:39], v[140:143], v[192:195], v[36:39]
	v_mfma_f32_16x16x32_bf16 v[16:19], v[132:135], v[200:203], v[16:19]
	v_mfma_f32_16x16x32_bf16 v[20:23], v[140:143], v[200:203], v[20:23]
	v_mfma_f32_16x16x32_bf16 v[0:3], v[132:135], v[208:211], v[0:3]
	v_mfma_f32_16x16x32_bf16 v[4:7], v[140:143], v[208:211], v[4:7]
	s_setprio 0
	s_setprio 1
	v_mfma_f32_16x16x32_bf16 v[56:59], v[158:161], v[180:183], v[56:59]
	v_mfma_f32_16x16x32_bf16 v[60:63], v[172:175], v[180:183], v[60:63]
	v_mfma_f32_16x16x32_bf16 v[40:43], v[158:161], v[188:191], v[40:43]
	v_mfma_f32_16x16x32_bf16 v[44:47], v[172:175], v[188:191], v[44:47]
	v_mfma_f32_16x16x32_bf16 v[24:27], v[158:161], v[196:199], v[24:27]
	v_mfma_f32_16x16x32_bf16 v[28:31], v[172:175], v[196:199], v[28:31]
	v_mfma_f32_16x16x32_bf16 v[8:11], v[158:161], v[204:207], v[8:11]
	v_mfma_f32_16x16x32_bf16 v[12:15], v[172:175], v[204:207], v[12:15]
	s_waitcnt vmcnt(8)
	v_mfma_f32_16x16x32_bf16 v[56:59], v[162:165], v[184:187], v[56:59]
	v_mfma_f32_16x16x32_bf16 v[60:63], v[176:179], v[184:187], v[60:63]
	v_mfma_f32_16x16x32_bf16 v[40:43], v[162:165], v[192:195], v[40:43]
	v_mfma_f32_16x16x32_bf16 v[44:47], v[176:179], v[192:195], v[44:47]
	v_mfma_f32_16x16x32_bf16 v[24:27], v[162:165], v[200:203], v[24:27]
	v_mfma_f32_16x16x32_bf16 v[28:31], v[176:179], v[200:203], v[28:31]
	v_mfma_f32_16x16x32_bf16 v[8:11], v[162:165], v[208:211], v[8:11]
	v_mfma_f32_16x16x32_bf16 v[12:15], v[176:179], v[208:211], v[12:15]
	s_barrier
	s_setprio 0
	s_add_i32 s37, 0, 0x18000
	s_add_i32 s38, 0, 0x1c000
	v_add_u32_e32 v140, s37, v167
	v_add_u32_e32 v176, s38, v167
	ds_read_b128 v[128:131], v140
	ds_read_b128 v[132:135], v140 offset:1024
	ds_read_b128 v[136:139], v140 offset:2048
	ds_read_b128 v[140:143], v140 offset:3072
	ds_read_b128 v[158:161], v176
	ds_read_b128 v[162:165], v176 offset:1024
	ds_read_b128 v[172:175], v176 offset:2048
	ds_read_b128 v[176:179], v176 offset:3072
	s_add_u32 s26, s26, 0x80000
	s_addc_u32 s27, s27, 0
	s_mov_b32 m0, s7
	v_lshl_add_u64 v[220:221], s[26:27], 0, v[150:151]
	ds_read_b128 v[180:183], v171 offset:32768
	ds_read_b128 v[184:187], v171 offset:33792
	ds_read_b128 v[188:191], v171 offset:34816
	ds_read_b128 v[192:195], v171 offset:35840
	ds_read_b128 v[196:199], v171 offset:36864
	ds_read_b128 v[200:203], v171 offset:37888
	ds_read_b128 v[204:207], v171 offset:38912
	ds_read_b128 v[208:211], v171 offset:39936
	global_load_lds_dwordx4 v[220:221], off
	v_lshl_add_u64 v[220:221], s[26:27], 0, v[146:147]
	s_mov_b32 m0, s19
	s_nop 0
	global_load_lds_dwordx4 v[220:221], off
	s_bitcmp1_b32 s97, 12
	s_cbranch_scc0 .Ldefer_15
	s_waitcnt vmcnt(8)

.Ldefer_16:
	s_waitcnt lgkmcnt(0)
	s_setprio 1
	s_barrier
	v_mfma_f32_16x16x32_bf16 v[48:51], v[128:131], v[180:183], v[48:51]
	v_mfma_f32_16x16x32_bf16 v[52:55], v[136:139], v[180:183], v[52:55]
	v_mfma_f32_16x16x32_bf16 v[32:35], v[128:131], v[188:191], v[32:35]
	v_mfma_f32_16x16x32_bf16 v[36:39], v[136:139], v[188:191], v[36:39]
	v_mfma_f32_16x16x32_bf16 v[16:19], v[128:131], v[196:199], v[16:19]
	v_mfma_f32_16x16x32_bf16 v[20:23], v[136:139], v[196:199], v[20:23]
	v_mfma_f32_16x16x32_bf16 v[0:3], v[128:131], v[204:207], v[0:3]
	v_mfma_f32_16x16x32_bf16 v[4:7], v[136:139], v[204:207], v[4:7]
	v_mfma_f32_16x16x32_bf16 v[48:51], v[132:135], v[184:187], v[48:51]
	v_mfma_f32_16x16x32_bf16 v[52:55], v[140:143], v[184:187], v[52:55]
	v_mfma_f32_16x16x32_bf16 v[32:35], v[132:135], v[192:195], v[32:35]
	v_mfma_f32_16x16x32_bf16 v[36:39], v[140:143], v[192:195], v[36:39]
	v_mfma_f32_16x16x32_bf16 v[16:19], v[132:135], v[200:203], v[16:19]
	v_mfma_f32_16x16x32_bf16 v[20:23], v[140:143], v[200:203], v[20:23]
	v_mfma_f32_16x16x32_bf16 v[0:3], v[132:135], v[208:211], v[0:3]
	v_mfma_f32_16x16x32_bf16 v[4:7], v[140:143], v[208:211], v[4:7]
	s_setprio 0
	s_setprio 1
	v_mfma_f32_16x16x32_bf16 v[56:59], v[158:161], v[180:183], v[56:59]
	v_mfma_f32_16x16x32_bf16 v[60:63], v[172:175], v[180:183], v[60:63]
	v_mfma_f32_16x16x32_bf16 v[40:43], v[158:161], v[188:191], v[40:43]
	v_mfma_f32_16x16x32_bf16 v[44:47], v[172:175], v[188:191], v[44:47]
	v_mfma_f32_16x16x32_bf16 v[24:27], v[158:161], v[196:199], v[24:27]
	v_mfma_f32_16x16x32_bf16 v[28:31], v[172:175], v[196:199], v[28:31]
	v_mfma_f32_16x16x32_bf16 v[8:11], v[158:161], v[204:207], v[8:11]
	v_mfma_f32_16x16x32_bf16 v[12:15], v[172:175], v[204:207], v[12:15]
	s_waitcnt vmcnt(8)
	v_mfma_f32_16x16x32_bf16 v[56:59], v[162:165], v[184:187], v[56:59]
	v_mfma_f32_16x16x32_bf16 v[60:63], v[176:179], v[184:187], v[60:63]
	v_mfma_f32_16x16x32_bf16 v[40:43], v[162:165], v[192:195], v[40:43]
	v_mfma_f32_16x16x32_bf16 v[44:47], v[176:179], v[192:195], v[44:47]
	v_mfma_f32_16x16x32_bf16 v[24:27], v[162:165], v[200:203], v[24:27]
	v_mfma_f32_16x16x32_bf16 v[28:31], v[176:179], v[200:203], v[28:31]
	v_mfma_f32_16x16x32_bf16 v[8:11], v[162:165], v[208:211], v[8:11]
	v_mfma_f32_16x16x32_bf16 v[12:15], v[176:179], v[208:211], v[12:15]
	s_barrier
	s_setprio 0
	s_add_i32 s36, s36, 2
	s_add_u32 s34, s34, 0x100
	s_addc_u32 s35, s35, 0
	s_add_u32 s22, s22, 0x100
	s_addc_u32 s23, s23, 0
	s_cmp_gt_u32 s36, 5
	s_cbranch_scc0 .LBB0_1693

.LBB0_2019:
	s_cmp_lt_u32 s5, 0x3fffffff
	s_cselect_b64 s[40:41], -1, 0
	s_ashr_i32 s23, s22, 31
	s_and_b64 s[40:41], s[36:37], s[40:41]
	s_lshl_b64 s[36:37], s[22:23], 21
	s_add_u32 s5, s86, s36
	s_addc_u32 s21, s87, s37
	s_add_u32 s36, s5, s38
	s_addc_u32 s37, s21, s39
	s_and_b64 s[48:49], s[40:41], exec
	s_cselect_b32 s5, s37, s47
	s_cselect_b32 s23, s36, s46
	s_ashr_i32 s21, s20, 31
	s_lshl_b64 s[48:49], s[20:21], 21
	v_readlane_b32 s68, v254, 13
	v_readlane_b32 s69, v254, 14
	s_add_u32 s21, s68, s48
	s_addc_u32 s43, s69, s49
	s_add_u32 s38, s21, s38
	s_addc_u32 s39, s43, s39
	s_and_b64 s[48:49], s[40:41], exec
	s_cselect_b32 s21, s39, s45
	s_cselect_b32 s43, s38, s44
	s_add_i32 s68, s67, -2
	s_add_u32 s69, s44, 0x100
	s_addc_u32 s70, s45, 0
	s_add_u32 s44, s46, 0x100080
	s_addc_u32 s45, s47, 0
	s_mov_b32 s46, 0
	s_waitcnt vmcnt(0)
	ds_read_b128 v[128:131], v244
	ds_read_b128 v[132:135], v244 offset:1024
	ds_read_b128 v[136:139], v244 offset:2048
	ds_read_b128 v[140:143], v244 offset:3072
	ds_read_b128 v[144:147], v245
	ds_read_b128 v[148:151], v245 offset:1024
	ds_read_b128 v[152:155], v245 offset:2048
	ds_read_b128 v[156:159], v245 offset:3072
	s_add_i32 s71, s46, 2
	s_add_u32 s47, s44, 0xfff00080
	s_addc_u32 s48, s45, -1
	s_cmp_eq_u32 s68, s46
	s_cselect_b32 s46, s43, s69
	s_cselect_b32 s49, s5, s48
	s_cselect_b32 s48, s23, s47
	s_cselect_b32 s47, s21, s70
	v_lshl_add_u64 v[192:193], s[44:45], 0, v[218:219]
	s_add_i32 m0, s94, 0xc000
	ds_read_b128 v[160:163], v246
	ds_read_b128 v[164:167], v246 offset:1024
	ds_read_b128 v[168:171], v246 offset:2048
	ds_read_b128 v[172:175], v246 offset:3072
	ds_read_b128 v[176:179], v246 offset:4096
	ds_read_b128 v[180:183], v246 offset:5120
	ds_read_b128 v[184:187], v246 offset:6144
	ds_read_b128 v[188:191], v246 offset:7168
	global_load_lds_dwordx4 v[192:193], off
	v_lshl_add_u64 v[192:193], s[44:45], 0, v[220:221]
	s_add_i32 m0, s94, 0xe000
	s_nop 0
	global_load_lds_dwordx4 v[192:193], off
	s_bitcmp1_b32 s97, 12
	s_cbranch_scc0 .Ldefer_17
	s_waitcnt vmcnt(8)
.Ldefer_17:
	s_waitcnt lgkmcnt(0)
	s_setprio 1
	s_barrier
	v_mfma_f32_16x16x32_bf16 v[112:115], v[128:131], v[160:163], 0
	v_mfma_f32_16x16x32_bf16 v[116:119], v[136:139], v[160:163], 0
	v_mfma_f32_16x16x32_bf16 v[100:103], v[128:131], v[168:171], 0
	v_mfma_f32_16x16x32_bf16 v[96:99], v[136:139], v[168:171], 0
	v_mfma_f32_16x16x32_bf16 v[84:87], v[128:131], v[176:179], 0
	v_mfma_f32_16x16x32_bf16 v[80:83], v[136:139], v[176:179], 0
	v_mfma_f32_16x16x32_bf16 v[52:55], v[128:131], v[184:187], 0
	v_mfma_f32_16x16x32_bf16 v[48:51], v[136:139], v[184:187], 0
	v_mfma_f32_16x16x32_bf16 v[112:115], v[132:135], v[164:167], v[112:115]
	v_mfma_f32_16x16x32_bf16 v[116:119], v[140:143], v[164:167], v[116:119]
	v_mfma_f32_16x16x32_bf16 v[100:103], v[132:135], v[172:175], v[100:103]
	v_mfma_f32_16x16x32_bf16 v[96:99], v[140:143], v[172:175], v[96:99]
	v_mfma_f32_16x16x32_bf16 v[84:87], v[132:135], v[180:183], v[84:87]
	v_mfma_f32_16x16x32_bf16 v[80:83], v[140:143], v[180:183], v[80:83]
	v_mfma_f32_16x16x32_bf16 v[52:55], v[132:135], v[188:191], v[52:55]
	v_mfma_f32_16x16x32_bf16 v[48:51], v[140:143], v[188:191], v[48:51]
	s_setprio 0
	s_setprio 1
	v_mfma_f32_16x16x32_bf16 v[124:127], v[144:147], v[160:163], 0
	v_mfma_f32_16x16x32_bf16 v[120:123], v[152:155], v[160:163], 0
	v_mfma_f32_16x16x32_bf16 v[108:111], v[144:147], v[168:171], 0
	v_mfma_f32_16x16x32_bf16 v[104:107], v[152:155], v[168:171], 0
	v_mfma_f32_16x16x32_bf16 v[92:95], v[144:147], v[176:179], 0
	v_mfma_f32_16x16x32_bf16 v[88:91], v[152:155], v[176:179], 0
	v_mfma_f32_16x16x32_bf16 v[68:71], v[144:147], v[184:187], 0
	v_mfma_f32_16x16x32_bf16 v[64:67], v[152:155], v[184:187], 0
	s_waitcnt vmcnt(8)
	v_mfma_f32_16x16x32_bf16 v[124:127], v[148:151], v[164:167], v[124:127]
	v_mfma_f32_16x16x32_bf16 v[120:123], v[156:159], v[164:167], v[120:123]
	v_mfma_f32_16x16x32_bf16 v[108:111], v[148:151], v[172:175], v[108:111]
	v_mfma_f32_16x16x32_bf16 v[104:107], v[156:159], v[172:175], v[104:107]
	v_mfma_f32_16x16x32_bf16 v[92:95], v[148:151], v[180:183], v[92:95]
	v_mfma_f32_16x16x32_bf16 v[88:91], v[156:159], v[180:183], v[88:91]
	v_mfma_f32_16x16x32_bf16 v[68:71], v[148:151], v[188:191], v[68:71]
	v_mfma_f32_16x16x32_bf16 v[64:67], v[156:159], v[188:191], v[64:67]
	s_barrier
	s_setprio 0
	s_add_i32 s76, s60, s97
	v_lshl_add_u64 v[192:193], s[46:47], 0, v[210:211]
	s_mov_b32 m0, s76
	ds_read_b128 v[160:163], v246 offset:16384
	ds_read_b128 v[164:167], v246 offset:17408
	ds_read_b128 v[168:171], v246 offset:18432
	ds_read_b128 v[172:175], v246 offset:19456
	ds_read_b128 v[176:179], v246 offset:20480
	ds_read_b128 v[180:183], v246 offset:21504
	ds_read_b128 v[184:187], v246 offset:22528
	ds_read_b128 v[188:191], v246 offset:23552
	global_load_lds_dwordx4 v[192:193], off
	s_add_i32 m0, s76, 0x2000
	s_add_u32 s76, s46, 0x100000
	v_lshl_add_u64 v[194:195], s[46:47], 0, v[214:215]
	s_addc_u32 s77, s47, 0
	s_add_i32 s78, s61, s97
	global_load_lds_dwordx4 v[194:195], off
	v_lshl_add_u64 v[196:197], s[76:77], 0, v[210:211]
	s_mov_b32 m0, s78
	v_lshl_add_u64 v[198:199], s[48:49], 0, v[212:213]
	global_load_lds_dwordx4 v[196:197], off
	v_lshl_add_u64 v[196:197], s[76:77], 0, v[214:215]
	s_add_i32 m0, s78, 0x2000
	s_nop 0
	global_load_lds_dwordx4 v[196:197], off
	v_lshl_add_u64 v[196:197], s[48:49], 0, v[208:209]
	s_mov_b32 m0, s94
	s_nop 0
	global_load_lds_dwordx4 v[196:197], off
	s_mov_b32 m0, s2
	s_nop 0
	global_load_lds_dwordx4 v[198:199], off
	s_bitcmp1_b32 s97, 12
	s_cbranch_scc0 .Ldefer_18
	s_waitcnt vmcnt(8)
.Ldefer_18:
	s_waitcnt lgkmcnt(0)
	s_setprio 1
	s_barrier
	v_mfma_f32_16x16x32_bf16 v[60:63], v[128:131], v[160:163], 0
	v_mfma_f32_16x16x32_bf16 v[56:59], v[136:139], v[160:163], 0
	v_mfma_f32_16x16x32_bf16 v[36:39], v[128:131], v[168:171], 0
	v_mfma_f32_16x16x32_bf16 v[32:35], v[136:139], v[168:171], 0
	v_mfma_f32_16x16x32_bf16 v[20:23], v[128:131], v[176:179], 0
	v_mfma_f32_16x16x32_bf16 v[16:19], v[136:139], v[176:179], 0
	v_mfma_f32_16x16x32_bf16 v[4:7], v[128:131], v[184:187], 0
	v_mfma_f32_16x16x32_bf16 v[0:3], v[136:139], v[184:187], 0
	v_mfma_f32_16x16x32_bf16 v[60:63], v[132:135], v[164:167], v[60:63]
	v_mfma_f32_16x16x32_bf16 v[56:59], v[140:143], v[164:167], v[56:59]
	v_mfma_f32_16x16x32_bf16 v[36:39], v[132:135], v[172:175], v[36:39]
	v_mfma_f32_16x16x32_bf16 v[32:35], v[140:143], v[172:175], v[32:35]
	v_mfma_f32_16x16x32_bf16 v[20:23], v[132:135], v[180:183], v[20:23]
	v_mfma_f32_16x16x32_bf16 v[16:19], v[140:143], v[180:183], v[16:19]
	v_mfma_f32_16x16x32_bf16 v[4:7], v[132:135], v[188:191], v[4:7]
	v_mfma_f32_16x16x32_bf16 v[0:3], v[140:143], v[188:191], v[0:3]
	s_setprio 0
	s_setprio 1
	v_mfma_f32_16x16x32_bf16 v[76:79], v[144:147], v[160:163], 0
	v_mfma_f32_16x16x32_bf16 v[72:75], v[152:155], v[160:163], 0
	v_mfma_f32_16x16x32_bf16 v[44:47], v[144:147], v[168:171], 0
	v_mfma_f32_16x16x32_bf16 v[40:43], v[152:155], v[168:171], 0
	v_mfma_f32_16x16x32_bf16 v[28:31], v[144:147], v[176:179], 0
	v_mfma_f32_16x16x32_bf16 v[24:27], v[152:155], v[176:179], 0
	v_mfma_f32_16x16x32_bf16 v[12:15], v[144:147], v[184:187], 0
	v_mfma_f32_16x16x32_bf16 v[8:11], v[152:155], v[184:187], 0
	s_waitcnt vmcnt(8)
	v_mfma_f32_16x16x32_bf16 v[76:79], v[148:151], v[164:167], v[76:79]
	v_mfma_f32_16x16x32_bf16 v[72:75], v[156:159], v[164:167], v[72:75]
	v_mfma_f32_16x16x32_bf16 v[44:47], v[148:151], v[172:175], v[44:47]
	v_mfma_f32_16x16x32_bf16 v[40:43], v[156:159], v[172:175], v[40:43]
	v_mfma_f32_16x16x32_bf16 v[28:31], v[148:151], v[180:183], v[28:31]
	v_mfma_f32_16x16x32_bf16 v[24:27], v[156:159], v[180:183], v[24:27]
	v_mfma_f32_16x16x32_bf16 v[12:15], v[148:151], v[188:191], v[12:15]
	v_mfma_f32_16x16x32_bf16 v[8:11], v[156:159], v[188:191], v[8:11]
	s_barrier
	s_setprio 0
	s_add_i32 s76, 0, 0x18000
	s_add_i32 s77, 0, 0x1c000
	v_add_u32_e32 v140, s76, v243
	v_add_u32_e32 v156, s77, v243
	ds_read_b128 v[128:131], v140
	ds_read_b128 v[132:135], v140 offset:1024
	ds_read_b128 v[136:139], v140 offset:2048
	ds_read_b128 v[140:143], v140 offset:3072
	ds_read_b128 v[144:147], v156
	ds_read_b128 v[148:151], v156 offset:1024
	ds_read_b128 v[152:155], v156 offset:2048
	ds_read_b128 v[156:159], v156 offset:3072
	s_add_u32 s48, s48, 0x100000
	s_addc_u32 s49, s49, 0
	s_mov_b32 m0, s3
	v_lshl_add_u64 v[200:201], s[48:49], 0, v[208:209]
	ds_read_b128 v[160:163], v246 offset:32768
	ds_read_b128 v[164:167], v246 offset:33792
	ds_read_b128 v[168:171], v246 offset:34816
	ds_read_b128 v[172:175], v246 offset:35840
	ds_read_b128 v[176:179], v246 offset:36864
	ds_read_b128 v[180:183], v246 offset:37888
	ds_read_b128 v[184:187], v246 offset:38912
	ds_read_b128 v[188:191], v246 offset:39936
	global_load_lds_dwordx4 v[200:201], off
	v_lshl_add_u64 v[200:201], s[48:49], 0, v[212:213]
	s_mov_b32 m0, s33
	s_nop 0
	global_load_lds_dwordx4 v[200:201], off
	s_bitcmp1_b32 s97, 12
	s_cbranch_scc0 .Ldefer_19
	s_waitcnt vmcnt(8)
.Ldefer_19:
	s_waitcnt lgkmcnt(0)
	s_setprio 1
	s_barrier
	v_mfma_f32_16x16x32_bf16 v[112:115], v[128:131], v[160:163], v[112:115]
	v_mfma_f32_16x16x32_bf16 v[116:119], v[136:139], v[160:163], v[116:119]
	v_mfma_f32_16x16x32_bf16 v[100:103], v[128:131], v[168:171], v[100:103]
	v_mfma_f32_16x16x32_bf16 v[96:99], v[136:139], v[168:171], v[96:99]
	v_mfma_f32_16x16x32_bf16 v[84:87], v[128:131], v[176:179], v[84:87]
	v_mfma_f32_16x16x32_bf16 v[80:83], v[136:139], v[176:179], v[80:83]
	v_mfma_f32_16x16x32_bf16 v[52:55], v[128:131], v[184:187], v[52:55]
	v_mfma_f32_16x16x32_bf16 v[48:51], v[136:139], v[184:187], v[48:51]
	v_mfma_f32_16x16x32_bf16 v[112:115], v[132:135], v[164:167], v[112:115]
	v_mfma_f32_16x16x32_bf16 v[116:119], v[140:143], v[164:167], v[116:119]
	v_mfma_f32_16x16x32_bf16 v[100:103], v[132:135], v[172:175], v[100:103]
	v_mfma_f32_16x16x32_bf16 v[96:99], v[140:143], v[172:175], v[96:99]
	v_mfma_f32_16x16x32_bf16 v[84:87], v[132:135], v[180:183], v[84:87]
	v_mfma_f32_16x16x32_bf16 v[80:83], v[140:143], v[180:183], v[80:83]
	v_mfma_f32_16x16x32_bf16 v[52:55], v[132:135], v[188:191], v[52:55]
	v_mfma_f32_16x16x32_bf16 v[48:51], v[140:143], v[188:191], v[48:51]
	s_setprio 0
	s_setprio 1
	v_mfma_f32_16x16x32_bf16 v[124:127], v[144:147], v[160:163], v[124:127]
	v_mfma_f32_16x16x32_bf16 v[120:123], v[152:155], v[160:163], v[120:123]
	v_mfma_f32_16x16x32_bf16 v[108:111], v[144:147], v[168:171], v[108:111]
	v_mfma_f32_16x16x32_bf16 v[104:107], v[152:155], v[168:171], v[104:107]
	v_mfma_f32_16x16x32_bf16 v[92:95], v[144:147], v[176:179], v[92:95]
	v_mfma_f32_16x16x32_bf16 v[88:91], v[152:155], v[176:179], v[88:91]
	v_mfma_f32_16x16x32_bf16 v[68:71], v[144:147], v[184:187], v[68:71]
	v_mfma_f32_16x16x32_bf16 v[64:67], v[152:155], v[184:187], v[64:67]
	s_waitcnt vmcnt(8)
	v_mfma_f32_16x16x32_bf16 v[124:127], v[148:151], v[164:167], v[124:127]
	v_mfma_f32_16x16x32_bf16 v[120:123], v[156:159], v[164:167], v[120:123]
	v_mfma_f32_16x16x32_bf16 v[108:111], v[148:151], v[172:175], v[108:111]
	v_mfma_f32_16x16x32_bf16 v[104:107], v[156:159], v[172:175], v[104:107]
	v_mfma_f32_16x16x32_bf16 v[92:95], v[148:151], v[180:183], v[92:95]
	v_mfma_f32_16x16x32_bf16 v[88:91], v[156:159], v[180:183], v[88:91]
	v_mfma_f32_16x16x32_bf16 v[68:71], v[148:151], v[188:191], v[68:71]
	v_mfma_f32_16x16x32_bf16 v[64:67], v[156:159], v[188:191], v[64:67]
	s_barrier
	s_setprio 0
	s_add_i32 s48, s76, s97
	v_lshl_add_u64 v[192:193], v[192:193], 0, s[16:17]
	s_mov_b32 m0, s48
	ds_read_b128 v[160:163], v246 offset:49152
	ds_read_b128 v[164:167], v246 offset:50176
	ds_read_b128 v[168:171], v246 offset:51200
	ds_read_b128 v[172:175], v246 offset:52224
	ds_read_b128 v[176:179], v246 offset:53248
	ds_read_b128 v[180:183], v246 offset:54272
	ds_read_b128 v[184:187], v246 offset:55296
	ds_read_b128 v[188:191], v246 offset:56320
	global_load_lds_dwordx4 v[192:193], off
	s_add_i32 m0, s48, 0x2000
	s_add_u32 s46, s46, 0x100080
	v_lshl_add_u64 v[192:193], v[194:195], 0, s[16:17]
	s_addc_u32 s47, s47, 0
	s_add_i32 s48, s77, s97
	global_load_lds_dwordx4 v[192:193], off
	v_lshl_add_u64 v[192:193], s[46:47], 0, v[210:211]
	s_mov_b32 m0, s48
	s_nop 0
	global_load_lds_dwordx4 v[192:193], off
	v_lshl_add_u64 v[192:193], s[46:47], 0, v[214:215]
	s_add_i32 m0, s48, 0x2000
	s_nop 0
	global_load_lds_dwordx4 v[192:193], off
	v_lshl_add_u64 v[192:193], v[196:197], 0, s[16:17]
	s_mov_b32 m0, s54
	s_nop 0
	global_load_lds_dwordx4 v[192:193], off
	v_lshl_add_u64 v[192:193], v[198:199], 0, s[16:17]
	s_mov_b32 m0, s55
	s_nop 0
	global_load_lds_dwordx4 v[192:193], off
	s_bitcmp1_b32 s97, 12
	s_cbranch_scc0 .Ldefer_20
	s_waitcnt vmcnt(8)
.Ldefer_20:
	s_waitcnt lgkmcnt(0)
	s_setprio 1
	s_barrier
	v_mfma_f32_16x16x32_bf16 v[60:63], v[128:131], v[160:163], v[60:63]
	v_mfma_f32_16x16x32_bf16 v[56:59], v[136:139], v[160:163], v[56:59]
	v_mfma_f32_16x16x32_bf16 v[36:39], v[128:131], v[168:171], v[36:39]
	v_mfma_f32_16x16x32_bf16 v[32:35], v[136:139], v[168:171], v[32:35]
	v_mfma_f32_16x16x32_bf16 v[20:23], v[128:131], v[176:179], v[20:23]
	v_mfma_f32_16x16x32_bf16 v[16:19], v[136:139], v[176:179], v[16:19]
	v_mfma_f32_16x16x32_bf16 v[4:7], v[128:131], v[184:187], v[4:7]
	v_mfma_f32_16x16x32_bf16 v[0:3], v[136:139], v[184:187], v[0:3]
	v_mfma_f32_16x16x32_bf16 v[60:63], v[132:135], v[164:167], v[60:63]
	v_mfma_f32_16x16x32_bf16 v[56:59], v[140:143], v[164:167], v[56:59]
	v_mfma_f32_16x16x32_bf16 v[36:39], v[132:135], v[172:175], v[36:39]
	v_mfma_f32_16x16x32_bf16 v[32:35], v[140:143], v[172:175], v[32:35]
	v_mfma_f32_16x16x32_bf16 v[20:23], v[132:135], v[180:183], v[20:23]
	v_mfma_f32_16x16x32_bf16 v[16:19], v[140:143], v[180:183], v[16:19]
	v_mfma_f32_16x16x32_bf16 v[4:7], v[132:135], v[188:191], v[4:7]
	v_mfma_f32_16x16x32_bf16 v[0:3], v[140:143], v[188:191], v[0:3]
	s_setprio 0
	s_setprio 1
	v_mfma_f32_16x16x32_bf16 v[76:79], v[144:147], v[160:163], v[76:79]
	v_mfma_f32_16x16x32_bf16 v[72:75], v[152:155], v[160:163], v[72:75]
	v_mfma_f32_16x16x32_bf16 v[44:47], v[144:147], v[168:171], v[44:47]
	v_mfma_f32_16x16x32_bf16 v[40:43], v[152:155], v[168:171], v[40:43]
	v_mfma_f32_16x16x32_bf16 v[28:31], v[144:147], v[176:179], v[28:31]
	v_mfma_f32_16x16x32_bf16 v[24:27], v[152:155], v[176:179], v[24:27]
	v_mfma_f32_16x16x32_bf16 v[12:15], v[144:147], v[184:187], v[12:15]
	v_mfma_f32_16x16x32_bf16 v[8:11], v[152:155], v[184:187], v[8:11]
	s_waitcnt vmcnt(8)
	v_mfma_f32_16x16x32_bf16 v[76:79], v[148:151], v[164:167], v[76:79]
	v_mfma_f32_16x16x32_bf16 v[72:75], v[156:159], v[164:167], v[72:75]
	v_mfma_f32_16x16x32_bf16 v[44:47], v[148:151], v[172:175], v[44:47]
	v_mfma_f32_16x16x32_bf16 v[40:43], v[156:159], v[172:175], v[40:43]
	v_mfma_f32_16x16x32_bf16 v[28:31], v[148:151], v[180:183], v[28:31]
	v_mfma_f32_16x16x32_bf16 v[24:27], v[156:159], v[180:183], v[24:27]
	v_mfma_f32_16x16x32_bf16 v[12:15], v[148:151], v[188:191], v[12:15]
	v_mfma_f32_16x16x32_bf16 v[8:11], v[156:159], v[188:191], v[8:11]
	s_barrier
	s_setprio 0
	s_add_u32 s69, s69, 0x100
	s_addc_u32 s70, s70, 0
	s_add_u32 s44, s44, 0x100
	s_addc_u32 s45, s45, 0
	s_cmp_ge_u32 s71, s67
	s_mov_b32 s46, s71
	s_cbranch_scc1 .Lpeel_done_2
.LBB0_2020:
	ds_read_b128 v[128:131], v244
	ds_read_b128 v[132:135], v244 offset:1024
	ds_read_b128 v[136:139], v244 offset:2048
	ds_read_b128 v[140:143], v244 offset:3072
	ds_read_b128 v[144:147], v245
	ds_read_b128 v[148:151], v245 offset:1024
	ds_read_b128 v[152:155], v245 offset:2048
	ds_read_b128 v[156:159], v245 offset:3072
	s_add_i32 s71, s46, 2
	s_add_u32 s47, s44, 0xfff00080
	s_addc_u32 s48, s45, -1
	s_cmp_eq_u32 s68, s46
	s_cselect_b32 s46, s43, s69
	s_cselect_b32 s49, s5, s48
	s_cselect_b32 s48, s23, s47
	s_cselect_b32 s47, s21, s70
	v_lshl_add_u64 v[192:193], s[44:45], 0, v[218:219]
	s_add_i32 m0, s94, 0xc000
	ds_read_b128 v[160:163], v246
	ds_read_b128 v[164:167], v246 offset:1024
	ds_read_b128 v[168:171], v246 offset:2048
	ds_read_b128 v[172:175], v246 offset:3072
	ds_read_b128 v[176:179], v246 offset:4096
	ds_read_b128 v[180:183], v246 offset:5120
	ds_read_b128 v[184:187], v246 offset:6144
	ds_read_b128 v[188:191], v246 offset:7168
	global_load_lds_dwordx4 v[192:193], off
	v_lshl_add_u64 v[192:193], s[44:45], 0, v[220:221]
	s_add_i32 m0, s94, 0xe000
	s_nop 0
	global_load_lds_dwordx4 v[192:193], off
	s_bitcmp1_b32 s97, 12
	s_cbranch_scc0 .Ldefer_21
	s_waitcnt vmcnt(8)
.Ldefer_21:
	s_waitcnt lgkmcnt(0)
	s_setprio 1
	s_barrier
	v_mfma_f32_16x16x32_bf16 v[112:115], v[128:131], v[160:163], v[112:115]
	v_mfma_f32_16x16x32_bf16 v[116:119], v[136:139], v[160:163], v[116:119]
	v_mfma_f32_16x16x32_bf16 v[100:103], v[128:131], v[168:171], v[100:103]
	v_mfma_f32_16x16x32_bf16 v[96:99], v[136:139], v[168:171], v[96:99]
	v_mfma_f32_16x16x32_bf16 v[84:87], v[128:131], v[176:179], v[84:87]
	v_mfma_f32_16x16x32_bf16 v[80:83], v[136:139], v[176:179], v[80:83]
	v_mfma_f32_16x16x32_bf16 v[52:55], v[128:131], v[184:187], v[52:55]
	v_mfma_f32_16x16x32_bf16 v[48:51], v[136:139], v[184:187], v[48:51]
	v_mfma_f32_16x16x32_bf16 v[112:115], v[132:135], v[164:167], v[112:115]
	v_mfma_f32_16x16x32_bf16 v[116:119], v[140:143], v[164:167], v[116:119]
	v_mfma_f32_16x16x32_bf16 v[100:103], v[132:135], v[172:175], v[100:103]
	v_mfma_f32_16x16x32_bf16 v[96:99], v[140:143], v[172:175], v[96:99]
	v_mfma_f32_16x16x32_bf16 v[84:87], v[132:135], v[180:183], v[84:87]
	v_mfma_f32_16x16x32_bf16 v[80:83], v[140:143], v[180:183], v[80:83]
	v_mfma_f32_16x16x32_bf16 v[52:55], v[132:135], v[188:191], v[52:55]
	v_mfma_f32_16x16x32_bf16 v[48:51], v[140:143], v[188:191], v[48:51]
	s_setprio 0
	s_setprio 1
	v_mfma_f32_16x16x32_bf16 v[124:127], v[144:147], v[160:163], v[124:127]
	v_mfma_f32_16x16x32_bf16 v[120:123], v[152:155], v[160:163], v[120:123]
	v_mfma_f32_16x16x32_bf16 v[108:111], v[144:147], v[168:171], v[108:111]
	v_mfma_f32_16x16x32_bf16 v[104:107], v[152:155], v[168:171], v[104:107]
	v_mfma_f32_16x16x32_bf16 v[92:95], v[144:147], v[176:179], v[92:95]
	v_mfma_f32_16x16x32_bf16 v[88:91], v[152:155], v[176:179], v[88:91]
	v_mfma_f32_16x16x32_bf16 v[68:71], v[144:147], v[184:187], v[68:71]
	v_mfma_f32_16x16x32_bf16 v[64:67], v[152:155], v[184:187], v[64:67]
	s_waitcnt vmcnt(8)
	v_mfma_f32_16x16x32_bf16 v[124:127], v[148:151], v[164:167], v[124:127]
	v_mfma_f32_16x16x32_bf16 v[120:123], v[156:159], v[164:167], v[120:123]
	v_mfma_f32_16x16x32_bf16 v[108:111], v[148:151], v[172:175], v[108:111]
	v_mfma_f32_16x16x32_bf16 v[104:107], v[156:159], v[172:175], v[104:107]
	v_mfma_f32_16x16x32_bf16 v[92:95], v[148:151], v[180:183], v[92:95]
	v_mfma_f32_16x16x32_bf16 v[88:91], v[156:159], v[180:183], v[88:91]
	v_mfma_f32_16x16x32_bf16 v[68:71], v[148:151], v[188:191], v[68:71]
	v_mfma_f32_16x16x32_bf16 v[64:67], v[156:159], v[188:191], v[64:67]
	s_barrier
	s_setprio 0
	s_add_i32 s76, s60, s97
	v_lshl_add_u64 v[192:193], s[46:47], 0, v[210:211]
	s_mov_b32 m0, s76
	ds_read_b128 v[160:163], v246 offset:16384
	ds_read_b128 v[164:167], v246 offset:17408
	ds_read_b128 v[168:171], v246 offset:18432
	ds_read_b128 v[172:175], v246 offset:19456
	ds_read_b128 v[176:179], v246 offset:20480
	ds_read_b128 v[180:183], v246 offset:21504
	ds_read_b128 v[184:187], v246 offset:22528
	ds_read_b128 v[188:191], v246 offset:23552
	global_load_lds_dwordx4 v[192:193], off
	s_add_i32 m0, s76, 0x2000
	s_add_u32 s76, s46, 0x100000
	v_lshl_add_u64 v[194:195], s[46:47], 0, v[214:215]
	s_addc_u32 s77, s47, 0
	s_add_i32 s78, s61, s97
	global_load_lds_dwordx4 v[194:195], off
	v_lshl_add_u64 v[196:197], s[76:77], 0, v[210:211]
	s_mov_b32 m0, s78
	v_lshl_add_u64 v[198:199], s[48:49], 0, v[212:213]
	global_load_lds_dwordx4 v[196:197], off
	v_lshl_add_u64 v[196:197], s[76:77], 0, v[214:215]
	s_add_i32 m0, s78, 0x2000
	s_nop 0
	global_load_lds_dwordx4 v[196:197], off
	v_lshl_add_u64 v[196:197], s[48:49], 0, v[208:209]
	s_mov_b32 m0, s94
	s_nop 0
	global_load_lds_dwordx4 v[196:197], off
	s_mov_b32 m0, s2
	s_nop 0
	global_load_lds_dwordx4 v[198:199], off
	s_bitcmp1_b32 s97, 12
	s_cbranch_scc0 .Ldefer_22
	s_waitcnt vmcnt(8)
.Ldefer_22:
	s_waitcnt lgkmcnt(0)
	s_setprio 1
	s_barrier
	v_mfma_f32_16x16x32_bf16 v[60:63], v[128:131], v[160:163], v[60:63]
	v_mfma_f32_16x16x32_bf16 v[56:59], v[136:139], v[160:163], v[56:59]
	v_mfma_f32_16x16x32_bf16 v[36:39], v[128:131], v[168:171], v[36:39]
	v_mfma_f32_16x16x32_bf16 v[32:35], v[136:139], v[168:171], v[32:35]
	v_mfma_f32_16x16x32_bf16 v[20:23], v[128:131], v[176:179], v[20:23]
	v_mfma_f32_16x16x32_bf16 v[16:19], v[136:139], v[176:179], v[16:19]
	v_mfma_f32_16x16x32_bf16 v[4:7], v[128:131], v[184:187], v[4:7]
	v_mfma_f32_16x16x32_bf16 v[0:3], v[136:139], v[184:187], v[0:3]
	v_mfma_f32_16x16x32_bf16 v[60:63], v[132:135], v[164:167], v[60:63]
	v_mfma_f32_16x16x32_bf16 v[56:59], v[140:143], v[164:167], v[56:59]
	v_mfma_f32_16x16x32_bf16 v[36:39], v[132:135], v[172:175], v[36:39]
	v_mfma_f32_16x16x32_bf16 v[32:35], v[140:143], v[172:175], v[32:35]
	v_mfma_f32_16x16x32_bf16 v[20:23], v[132:135], v[180:183], v[20:23]
	v_mfma_f32_16x16x32_bf16 v[16:19], v[140:143], v[180:183], v[16:19]
	v_mfma_f32_16x16x32_bf16 v[4:7], v[132:135], v[188:191], v[4:7]
	v_mfma_f32_16x16x32_bf16 v[0:3], v[140:143], v[188:191], v[0:3]
	s_setprio 0
	s_setprio 1
	v_mfma_f32_16x16x32_bf16 v[76:79], v[144:147], v[160:163], v[76:79]
	v_mfma_f32_16x16x32_bf16 v[72:75], v[152:155], v[160:163], v[72:75]
	v_mfma_f32_16x16x32_bf16 v[44:47], v[144:147], v[168:171], v[44:47]
	v_mfma_f32_16x16x32_bf16 v[40:43], v[152:155], v[168:171], v[40:43]
	v_mfma_f32_16x16x32_bf16 v[28:31], v[144:147], v[176:179], v[28:31]
	v_mfma_f32_16x16x32_bf16 v[24:27], v[152:155], v[176:179], v[24:27]
	v_mfma_f32_16x16x32_bf16 v[12:15], v[144:147], v[184:187], v[12:15]
	v_mfma_f32_16x16x32_bf16 v[8:11], v[152:155], v[184:187], v[8:11]
	s_waitcnt vmcnt(8)
	v_mfma_f32_16x16x32_bf16 v[76:79], v[148:151], v[164:167], v[76:79]
	v_mfma_f32_16x16x32_bf16 v[72:75], v[156:159], v[164:167], v[72:75]
	v_mfma_f32_16x16x32_bf16 v[44:47], v[148:151], v[172:175], v[44:47]
	v_mfma_f32_16x16x32_bf16 v[40:43], v[156:159], v[172:175], v[40:43]
	v_mfma_f32_16x16x32_bf16 v[28:31], v[148:151], v[180:183], v[28:31]
	v_mfma_f32_16x16x32_bf16 v[24:27], v[156:159], v[180:183], v[24:27]
	v_mfma_f32_16x16x32_bf16 v[12:15], v[148:151], v[188:191], v[12:15]
	v_mfma_f32_16x16x32_bf16 v[8:11], v[156:159], v[188:191], v[8:11]
	s_barrier
	s_setprio 0
	s_add_i32 s76, 0, 0x18000
	s_add_i32 s77, 0, 0x1c000
	v_add_u32_e32 v140, s76, v243
	v_add_u32_e32 v156, s77, v243
	ds_read_b128 v[128:131], v140
	ds_read_b128 v[132:135], v140 offset:1024
	ds_read_b128 v[136:139], v140 offset:2048
	ds_read_b128 v[140:143], v140 offset:3072
	ds_read_b128 v[144:147], v156
	ds_read_b128 v[148:151], v156 offset:1024
	ds_read_b128 v[152:155], v156 offset:2048
	ds_read_b128 v[156:159], v156 offset:3072
	s_add_u32 s48, s48, 0x100000
	s_addc_u32 s49, s49, 0
	s_mov_b32 m0, s3
	v_lshl_add_u64 v[200:201], s[48:49], 0, v[208:209]
	ds_read_b128 v[160:163], v246 offset:32768
	ds_read_b128 v[164:167], v246 offset:33792
	ds_read_b128 v[168:171], v246 offset:34816
	ds_read_b128 v[172:175], v246 offset:35840
	ds_read_b128 v[176:179], v246 offset:36864
	ds_read_b128 v[180:183], v246 offset:37888
	ds_read_b128 v[184:187], v246 offset:38912
	ds_read_b128 v[188:191], v246 offset:39936
	global_load_lds_dwordx4 v[200:201], off
	v_lshl_add_u64 v[200:201], s[48:49], 0, v[212:213]
	s_mov_b32 m0, s33
	s_nop 0
	global_load_lds_dwordx4 v[200:201], off
	s_bitcmp1_b32 s97, 12
	s_cbranch_scc0 .Ldefer_23
	s_waitcnt vmcnt(8)

.Ldefer_24:
	s_waitcnt lgkmcnt(0)
	s_setprio 1
	s_barrier
	v_mfma_f32_16x16x32_bf16 v[60:63], v[128:131], v[160:163], v[60:63]
	v_mfma_f32_16x16x32_bf16 v[56:59], v[136:139], v[160:163], v[56:59]
	v_mfma_f32_16x16x32_bf16 v[36:39], v[128:131], v[168:171], v[36:39]
	v_mfma_f32_16x16x32_bf16 v[32:35], v[136:139], v[168:171], v[32:35]
	v_mfma_f32_16x16x32_bf16 v[20:23], v[128:131], v[176:179], v[20:23]
	v_mfma_f32_16x16x32_bf16 v[16:19], v[136:139], v[176:179], v[16:19]
	v_mfma_f32_16x16x32_bf16 v[4:7], v[128:131], v[184:187], v[4:7]
	v_mfma_f32_16x16x32_bf16 v[0:3], v[136:139], v[184:187], v[0:3]
	v_mfma_f32_16x16x32_bf16 v[60:63], v[132:135], v[164:167], v[60:63]
	v_mfma_f32_16x16x32_bf16 v[56:59], v[140:143], v[164:167], v[56:59]
	v_mfma_f32_16x16x32_bf16 v[36:39], v[132:135], v[172:175], v[36:39]
	v_mfma_f32_16x16x32_bf16 v[32:35], v[140:143], v[172:175], v[32:35]
	v_mfma_f32_16x16x32_bf16 v[20:23], v[132:135], v[180:183], v[20:23]
	v_mfma_f32_16x16x32_bf16 v[16:19], v[140:143], v[180:183], v[16:19]
	v_mfma_f32_16x16x32_bf16 v[4:7], v[132:135], v[188:191], v[4:7]
	v_mfma_f32_16x16x32_bf16 v[0:3], v[140:143], v[188:191], v[0:3]
	s_setprio 0
	s_setprio 1
	v_mfma_f32_16x16x32_bf16 v[76:79], v[144:147], v[160:163], v[76:79]
	v_mfma_f32_16x16x32_bf16 v[72:75], v[152:155], v[160:163], v[72:75]
	v_mfma_f32_16x16x32_bf16 v[44:47], v[144:147], v[168:171], v[44:47]
	v_mfma_f32_16x16x32_bf16 v[40:43], v[152:155], v[168:171], v[40:43]
	v_mfma_f32_16x16x32_bf16 v[28:31], v[144:147], v[176:179], v[28:31]
	v_mfma_f32_16x16x32_bf16 v[24:27], v[152:155], v[176:179], v[24:27]
	v_mfma_f32_16x16x32_bf16 v[12:15], v[144:147], v[184:187], v[12:15]
	v_mfma_f32_16x16x32_bf16 v[8:11], v[152:155], v[184:187], v[8:11]
	s_waitcnt vmcnt(8)
	v_mfma_f32_16x16x32_bf16 v[76:79], v[148:151], v[164:167], v[76:79]
	v_mfma_f32_16x16x32_bf16 v[72:75], v[156:159], v[164:167], v[72:75]
	v_mfma_f32_16x16x32_bf16 v[44:47], v[148:151], v[172:175], v[44:47]
	v_mfma_f32_16x16x32_bf16 v[40:43], v[156:159], v[172:175], v[40:43]
	v_mfma_f32_16x16x32_bf16 v[28:31], v[148:151], v[180:183], v[28:31]
	v_mfma_f32_16x16x32_bf16 v[24:27], v[156:159], v[180:183], v[24:27]
	v_mfma_f32_16x16x32_bf16 v[12:15], v[148:151], v[188:191], v[12:15]
	v_mfma_f32_16x16x32_bf16 v[8:11], v[156:159], v[188:191], v[8:11]
	s_barrier
	s_setprio 0
	s_add_u32 s69, s69, 0x100
	s_addc_u32 s70, s70, 0
	s_add_u32 s44, s44, 0x100
	s_addc_u32 s45, s45, 0
	s_cmp_ge_u32 s71, s67
	s_mov_b32 s46, s71
	s_cbranch_scc0 .LBB0_2020

.LBB0_2288:
	s_ashr_i32 s25, s24, 31
	s_lshl_b64 s[86:87], s[24:25], 21
	v_readlane_b32 s88, v254, 52
	v_readlane_b32 s89, v254, 53
	s_add_u32 s5, s88, s86
	s_addc_u32 s25, s89, s87
	s_add_u32 s38, s5, s38
	s_addc_u32 s39, s25, s39
	s_and_b64 s[48:49], s[48:49], exec
	s_cselect_b32 s5, s39, s45
	s_cselect_b32 s25, s38, s44
	s_add_i32 s43, s84, -2
	s_add_u32 s85, s44, 0x100
	s_addc_u32 s86, s45, 0
	s_add_u32 s44, s46, 0x100080
	s_addc_u32 s45, s47, 0
	s_mov_b32 s46, 0
	ds_read_b128 v[148:151], v159
	ds_read_b128 v[164:167], v159 offset:1024
	ds_read_b128 v[168:171], v159 offset:2048
	ds_read_b128 v[172:175], v159 offset:3072
	ds_read_b128 v[176:179], v160
	ds_read_b128 v[180:183], v160 offset:1024
	ds_read_b128 v[184:187], v160 offset:2048
	ds_read_b128 v[188:191], v160 offset:3072
	s_add_i32 s87, s46, 2
	s_add_u32 s47, s44, 0xfff00080
	s_addc_u32 s48, s45, -1
	s_cmp_eq_u32 s43, s46
	s_cselect_b32 s46, s25, s85
	s_cselect_b32 s49, s37, s48
	s_cselect_b32 s48, s36, s47
	s_cselect_b32 s47, s5, s86
	v_lshl_add_u64 v[152:153], s[44:45], 0, v[142:143]
	s_add_i32 m0, s94, 0xc000
	ds_read_b128 v[192:195], v161
	ds_read_b128 v[196:199], v161 offset:1024
	ds_read_b128 v[200:203], v161 offset:2048
	ds_read_b128 v[204:207], v161 offset:3072
	ds_read_b128 v[208:211], v161 offset:4096
	ds_read_b128 v[212:215], v161 offset:5120
	ds_read_b128 v[216:219], v161 offset:6144
	ds_read_b128 v[220:223], v161 offset:7168
	global_load_lds_dwordx4 v[152:153], off
	v_lshl_add_u64 v[152:153], s[44:45], 0, v[144:145]
	s_add_i32 m0, s94, 0xe000
	s_nop 0
	global_load_lds_dwordx4 v[152:153], off
	s_bitcmp1_b32 s97, 12
	s_cbranch_scc0 .Ldefer_25
	s_waitcnt vmcnt(8)
.Ldefer_25:
	s_waitcnt lgkmcnt(0)
	s_setprio 1
	s_barrier
	v_mfma_f32_16x16x32_bf16 v[112:115], v[148:151], v[192:195], 0
	v_mfma_f32_16x16x32_bf16 v[116:119], v[168:171], v[192:195], 0
	v_mfma_f32_16x16x32_bf16 v[100:103], v[148:151], v[200:203], 0
	v_mfma_f32_16x16x32_bf16 v[96:99], v[168:171], v[200:203], 0
	v_mfma_f32_16x16x32_bf16 v[84:87], v[148:151], v[208:211], 0
	v_mfma_f32_16x16x32_bf16 v[80:83], v[168:171], v[208:211], 0
	v_mfma_f32_16x16x32_bf16 v[52:55], v[148:151], v[216:219], 0
	v_mfma_f32_16x16x32_bf16 v[48:51], v[168:171], v[216:219], 0
	v_mfma_f32_16x16x32_bf16 v[112:115], v[164:167], v[196:199], v[112:115]
	v_mfma_f32_16x16x32_bf16 v[116:119], v[172:175], v[196:199], v[116:119]
	v_mfma_f32_16x16x32_bf16 v[100:103], v[164:167], v[204:207], v[100:103]
	v_mfma_f32_16x16x32_bf16 v[96:99], v[172:175], v[204:207], v[96:99]
	v_mfma_f32_16x16x32_bf16 v[84:87], v[164:167], v[212:215], v[84:87]
	v_mfma_f32_16x16x32_bf16 v[80:83], v[172:175], v[212:215], v[80:83]
	v_mfma_f32_16x16x32_bf16 v[52:55], v[164:167], v[220:223], v[52:55]
	v_mfma_f32_16x16x32_bf16 v[48:51], v[172:175], v[220:223], v[48:51]
	s_setprio 0
	s_setprio 1
	v_mfma_f32_16x16x32_bf16 v[124:127], v[176:179], v[192:195], 0
	v_mfma_f32_16x16x32_bf16 v[120:123], v[184:187], v[192:195], 0
	v_mfma_f32_16x16x32_bf16 v[108:111], v[176:179], v[200:203], 0
	v_mfma_f32_16x16x32_bf16 v[104:107], v[184:187], v[200:203], 0
	v_mfma_f32_16x16x32_bf16 v[92:95], v[176:179], v[208:211], 0
	v_mfma_f32_16x16x32_bf16 v[88:91], v[184:187], v[208:211], 0
	v_mfma_f32_16x16x32_bf16 v[68:71], v[176:179], v[216:219], 0
	v_mfma_f32_16x16x32_bf16 v[64:67], v[184:187], v[216:219], 0
	s_waitcnt vmcnt(8)
	v_mfma_f32_16x16x32_bf16 v[124:127], v[180:183], v[196:199], v[124:127]
	v_mfma_f32_16x16x32_bf16 v[120:123], v[188:191], v[196:199], v[120:123]
	v_mfma_f32_16x16x32_bf16 v[108:111], v[180:183], v[204:207], v[108:111]
	v_mfma_f32_16x16x32_bf16 v[104:107], v[188:191], v[204:207], v[104:107]
	v_mfma_f32_16x16x32_bf16 v[92:95], v[180:183], v[212:215], v[92:95]
	v_mfma_f32_16x16x32_bf16 v[88:91], v[188:191], v[212:215], v[88:91]
	v_mfma_f32_16x16x32_bf16 v[68:71], v[180:183], v[220:223], v[68:71]
	v_mfma_f32_16x16x32_bf16 v[64:67], v[188:191], v[220:223], v[64:67]
	s_barrier
	s_setprio 0
	s_add_i32 s88, s77, s97
	v_lshl_add_u64 v[152:153], s[46:47], 0, v[132:133]
	s_mov_b32 m0, s88
	ds_read_b128 v[192:195], v161 offset:16384
	ds_read_b128 v[196:199], v161 offset:17408
	ds_read_b128 v[200:203], v161 offset:18432
	ds_read_b128 v[204:207], v161 offset:19456
	ds_read_b128 v[208:211], v161 offset:20480
	ds_read_b128 v[212:215], v161 offset:21504
	ds_read_b128 v[216:219], v161 offset:22528
	ds_read_b128 v[220:223], v161 offset:23552
	global_load_lds_dwordx4 v[152:153], off
	s_add_i32 m0, s88, 0x2000
	s_add_u32 s88, s46, 0x100000
	v_lshl_add_u64 v[224:225], s[46:47], 0, v[136:137]
	s_addc_u32 s89, s47, 0
	s_add_i32 s90, s78, s97
	global_load_lds_dwordx4 v[224:225], off
	v_lshl_add_u64 v[226:227], s[88:89], 0, v[132:133]
	s_mov_b32 m0, s90
	v_lshl_add_u64 v[228:229], s[48:49], 0, v[134:135]
	global_load_lds_dwordx4 v[226:227], off
	v_lshl_add_u64 v[226:227], s[88:89], 0, v[136:137]
	s_add_i32 m0, s90, 0x2000
	s_nop 0
	global_load_lds_dwordx4 v[226:227], off
	v_lshl_add_u64 v[226:227], s[48:49], 0, v[130:131]
	s_mov_b32 m0, s94
	s_nop 0
	global_load_lds_dwordx4 v[226:227], off
	s_mov_b32 m0, s52
	s_nop 0
	global_load_lds_dwordx4 v[228:229], off
	s_bitcmp1_b32 s97, 12
	s_cbranch_scc0 .Ldefer_26
	s_waitcnt vmcnt(8)
.Ldefer_26:
	s_waitcnt lgkmcnt(0)
	s_setprio 1
	s_barrier
	v_mfma_f32_16x16x32_bf16 v[60:63], v[148:151], v[192:195], 0
	v_mfma_f32_16x16x32_bf16 v[56:59], v[168:171], v[192:195], 0
	v_mfma_f32_16x16x32_bf16 v[36:39], v[148:151], v[200:203], 0
	v_mfma_f32_16x16x32_bf16 v[32:35], v[168:171], v[200:203], 0
	v_mfma_f32_16x16x32_bf16 v[20:23], v[148:151], v[208:211], 0
	v_mfma_f32_16x16x32_bf16 v[16:19], v[168:171], v[208:211], 0
	v_mfma_f32_16x16x32_bf16 v[4:7], v[148:151], v[216:219], 0
	v_mfma_f32_16x16x32_bf16 v[0:3], v[168:171], v[216:219], 0
	v_mfma_f32_16x16x32_bf16 v[60:63], v[164:167], v[196:199], v[60:63]
	v_mfma_f32_16x16x32_bf16 v[56:59], v[172:175], v[196:199], v[56:59]
	v_mfma_f32_16x16x32_bf16 v[36:39], v[164:167], v[204:207], v[36:39]
	v_mfma_f32_16x16x32_bf16 v[32:35], v[172:175], v[204:207], v[32:35]
	v_mfma_f32_16x16x32_bf16 v[20:23], v[164:167], v[212:215], v[20:23]
	v_mfma_f32_16x16x32_bf16 v[16:19], v[172:175], v[212:215], v[16:19]
	v_mfma_f32_16x16x32_bf16 v[4:7], v[164:167], v[220:223], v[4:7]
	v_mfma_f32_16x16x32_bf16 v[0:3], v[172:175], v[220:223], v[0:3]
	s_setprio 0
	s_setprio 1
	v_mfma_f32_16x16x32_bf16 v[76:79], v[176:179], v[192:195], 0
	v_mfma_f32_16x16x32_bf16 v[72:75], v[184:187], v[192:195], 0
	v_mfma_f32_16x16x32_bf16 v[44:47], v[176:179], v[200:203], 0
	v_mfma_f32_16x16x32_bf16 v[40:43], v[184:187], v[200:203], 0
	v_mfma_f32_16x16x32_bf16 v[28:31], v[176:179], v[208:211], 0
	v_mfma_f32_16x16x32_bf16 v[24:27], v[184:187], v[208:211], 0
	v_mfma_f32_16x16x32_bf16 v[12:15], v[176:179], v[216:219], 0
	v_mfma_f32_16x16x32_bf16 v[8:11], v[184:187], v[216:219], 0
	s_waitcnt vmcnt(8)
	v_mfma_f32_16x16x32_bf16 v[76:79], v[180:183], v[196:199], v[76:79]
	v_mfma_f32_16x16x32_bf16 v[72:75], v[188:191], v[196:199], v[72:75]
	v_mfma_f32_16x16x32_bf16 v[44:47], v[180:183], v[204:207], v[44:47]
	v_mfma_f32_16x16x32_bf16 v[40:43], v[188:191], v[204:207], v[40:43]
	v_mfma_f32_16x16x32_bf16 v[28:31], v[180:183], v[212:215], v[28:31]
	v_mfma_f32_16x16x32_bf16 v[24:27], v[188:191], v[212:215], v[24:27]
	v_mfma_f32_16x16x32_bf16 v[12:15], v[180:183], v[220:223], v[12:15]
	v_mfma_f32_16x16x32_bf16 v[8:11], v[188:191], v[220:223], v[8:11]
	s_barrier
	s_setprio 0
	s_add_i32 s88, 0, 0x18000
	v_add_u32_e32 v163, s88, v157
	s_add_i32 s89, 0, 0x1c000
	ds_read_b128 v[148:151], v163
	ds_read_b128 v[164:167], v163 offset:1024
	ds_read_b128 v[168:171], v163 offset:2048
	ds_read_b128 v[172:175], v163 offset:3072
	v_add_u32_e32 v163, s89, v157
	ds_read_b128 v[176:179], v163
	ds_read_b128 v[180:183], v163 offset:1024
	ds_read_b128 v[184:187], v163 offset:2048
	ds_read_b128 v[188:191], v163 offset:3072
	s_add_u32 s48, s48, 0x100000
	s_addc_u32 s49, s49, 0
	s_mov_b32 m0, s53
	v_lshl_add_u64 v[230:231], s[48:49], 0, v[130:131]
	ds_read_b128 v[192:195], v161 offset:32768
	ds_read_b128 v[196:199], v161 offset:33792
	ds_read_b128 v[200:203], v161 offset:34816
	ds_read_b128 v[204:207], v161 offset:35840
	ds_read_b128 v[208:211], v161 offset:36864
	ds_read_b128 v[212:215], v161 offset:37888
	ds_read_b128 v[216:219], v161 offset:38912
	ds_read_b128 v[220:223], v161 offset:39936
	global_load_lds_dwordx4 v[230:231], off
	v_lshl_add_u64 v[230:231], s[48:49], 0, v[134:135]
	s_mov_b32 m0, s54
	s_nop 0
	global_load_lds_dwordx4 v[230:231], off
	s_bitcmp1_b32 s97, 12
	s_cbranch_scc0 .Ldefer_27
	s_waitcnt vmcnt(8)
.Ldefer_27:
	s_waitcnt lgkmcnt(0)
	s_setprio 1
	s_barrier
	v_mfma_f32_16x16x32_bf16 v[112:115], v[148:151], v[192:195], v[112:115]
	v_mfma_f32_16x16x32_bf16 v[116:119], v[168:171], v[192:195], v[116:119]
	v_mfma_f32_16x16x32_bf16 v[100:103], v[148:151], v[200:203], v[100:103]
	v_mfma_f32_16x16x32_bf16 v[96:99], v[168:171], v[200:203], v[96:99]
	v_mfma_f32_16x16x32_bf16 v[84:87], v[148:151], v[208:211], v[84:87]
	v_mfma_f32_16x16x32_bf16 v[80:83], v[168:171], v[208:211], v[80:83]
	v_mfma_f32_16x16x32_bf16 v[52:55], v[148:151], v[216:219], v[52:55]
	v_mfma_f32_16x16x32_bf16 v[48:51], v[168:171], v[216:219], v[48:51]
	v_mfma_f32_16x16x32_bf16 v[112:115], v[164:167], v[196:199], v[112:115]
	v_mfma_f32_16x16x32_bf16 v[116:119], v[172:175], v[196:199], v[116:119]
	v_mfma_f32_16x16x32_bf16 v[100:103], v[164:167], v[204:207], v[100:103]
	v_mfma_f32_16x16x32_bf16 v[96:99], v[172:175], v[204:207], v[96:99]
	v_mfma_f32_16x16x32_bf16 v[84:87], v[164:167], v[212:215], v[84:87]
	v_mfma_f32_16x16x32_bf16 v[80:83], v[172:175], v[212:215], v[80:83]
	v_mfma_f32_16x16x32_bf16 v[52:55], v[164:167], v[220:223], v[52:55]
	v_mfma_f32_16x16x32_bf16 v[48:51], v[172:175], v[220:223], v[48:51]
	s_setprio 0
	s_setprio 1
	v_mfma_f32_16x16x32_bf16 v[124:127], v[176:179], v[192:195], v[124:127]
	v_mfma_f32_16x16x32_bf16 v[120:123], v[184:187], v[192:195], v[120:123]
	v_mfma_f32_16x16x32_bf16 v[108:111], v[176:179], v[200:203], v[108:111]
	v_mfma_f32_16x16x32_bf16 v[104:107], v[184:187], v[200:203], v[104:107]
	v_mfma_f32_16x16x32_bf16 v[92:95], v[176:179], v[208:211], v[92:95]
	v_mfma_f32_16x16x32_bf16 v[88:91], v[184:187], v[208:211], v[88:91]
	v_mfma_f32_16x16x32_bf16 v[68:71], v[176:179], v[216:219], v[68:71]
	v_mfma_f32_16x16x32_bf16 v[64:67], v[184:187], v[216:219], v[64:67]
	s_waitcnt vmcnt(8)
	v_mfma_f32_16x16x32_bf16 v[124:127], v[180:183], v[196:199], v[124:127]
	v_mfma_f32_16x16x32_bf16 v[120:123], v[188:191], v[196:199], v[120:123]
	v_mfma_f32_16x16x32_bf16 v[108:111], v[180:183], v[204:207], v[108:111]
	v_mfma_f32_16x16x32_bf16 v[104:107], v[188:191], v[204:207], v[104:107]
	v_mfma_f32_16x16x32_bf16 v[92:95], v[180:183], v[212:215], v[92:95]
	v_mfma_f32_16x16x32_bf16 v[88:91], v[188:191], v[212:215], v[88:91]
	v_mfma_f32_16x16x32_bf16 v[68:71], v[180:183], v[220:223], v[68:71]
	v_mfma_f32_16x16x32_bf16 v[64:67], v[188:191], v[220:223], v[64:67]
	s_barrier
	s_setprio 0
	s_add_i32 s48, s88, s97
	v_lshl_add_u64 v[152:153], v[152:153], 0, s[18:19]
	s_mov_b32 m0, s48
	ds_read_b128 v[192:195], v161 offset:49152
	ds_read_b128 v[196:199], v161 offset:50176
	ds_read_b128 v[200:203], v161 offset:51200
	ds_read_b128 v[204:207], v161 offset:52224
	ds_read_b128 v[208:211], v161 offset:53248
	ds_read_b128 v[212:215], v161 offset:54272
	ds_read_b128 v[216:219], v161 offset:55296
	ds_read_b128 v[220:223], v161 offset:56320
	global_load_lds_dwordx4 v[152:153], off
	s_add_i32 m0, s48, 0x2000
	s_add_u32 s46, s46, 0x100080
	v_lshl_add_u64 v[152:153], v[224:225], 0, s[18:19]
	s_addc_u32 s47, s47, 0
	s_add_i32 s48, s89, s97
	global_load_lds_dwordx4 v[152:153], off
	v_lshl_add_u64 v[152:153], s[46:47], 0, v[132:133]
	s_mov_b32 m0, s48
	s_nop 0
	global_load_lds_dwordx4 v[152:153], off
	v_lshl_add_u64 v[152:153], s[46:47], 0, v[136:137]
	s_add_i32 m0, s48, 0x2000
	s_nop 0
	global_load_lds_dwordx4 v[152:153], off
	v_lshl_add_u64 v[152:153], v[226:227], 0, s[18:19]
	s_mov_b32 m0, s68
	s_nop 0
	global_load_lds_dwordx4 v[152:153], off
	v_lshl_add_u64 v[152:153], v[228:229], 0, s[18:19]
	s_mov_b32 m0, s69
	s_nop 0
	global_load_lds_dwordx4 v[152:153], off
	s_bitcmp1_b32 s97, 12
	s_cbranch_scc0 .Ldefer_28
	s_waitcnt vmcnt(8)
.Ldefer_28:
	s_waitcnt lgkmcnt(0)
	s_setprio 1
	s_barrier
	v_mfma_f32_16x16x32_bf16 v[60:63], v[148:151], v[192:195], v[60:63]
	v_mfma_f32_16x16x32_bf16 v[56:59], v[168:171], v[192:195], v[56:59]
	v_mfma_f32_16x16x32_bf16 v[36:39], v[148:151], v[200:203], v[36:39]
	v_mfma_f32_16x16x32_bf16 v[32:35], v[168:171], v[200:203], v[32:35]
	v_mfma_f32_16x16x32_bf16 v[20:23], v[148:151], v[208:211], v[20:23]
	v_mfma_f32_16x16x32_bf16 v[16:19], v[168:171], v[208:211], v[16:19]
	v_mfma_f32_16x16x32_bf16 v[4:7], v[148:151], v[216:219], v[4:7]
	v_mfma_f32_16x16x32_bf16 v[0:3], v[168:171], v[216:219], v[0:3]
	v_mfma_f32_16x16x32_bf16 v[60:63], v[164:167], v[196:199], v[60:63]
	v_mfma_f32_16x16x32_bf16 v[56:59], v[172:175], v[196:199], v[56:59]
	v_mfma_f32_16x16x32_bf16 v[36:39], v[164:167], v[204:207], v[36:39]
	v_mfma_f32_16x16x32_bf16 v[32:35], v[172:175], v[204:207], v[32:35]
	v_mfma_f32_16x16x32_bf16 v[20:23], v[164:167], v[212:215], v[20:23]
	v_mfma_f32_16x16x32_bf16 v[16:19], v[172:175], v[212:215], v[16:19]
	v_mfma_f32_16x16x32_bf16 v[4:7], v[164:167], v[220:223], v[4:7]
	v_mfma_f32_16x16x32_bf16 v[0:3], v[172:175], v[220:223], v[0:3]
	s_setprio 0
	s_setprio 1
	v_mfma_f32_16x16x32_bf16 v[76:79], v[176:179], v[192:195], v[76:79]
	v_mfma_f32_16x16x32_bf16 v[72:75], v[184:187], v[192:195], v[72:75]
	v_mfma_f32_16x16x32_bf16 v[44:47], v[176:179], v[200:203], v[44:47]
	v_mfma_f32_16x16x32_bf16 v[40:43], v[184:187], v[200:203], v[40:43]
	v_mfma_f32_16x16x32_bf16 v[28:31], v[176:179], v[208:211], v[28:31]
	v_mfma_f32_16x16x32_bf16 v[24:27], v[184:187], v[208:211], v[24:27]
	v_mfma_f32_16x16x32_bf16 v[12:15], v[176:179], v[216:219], v[12:15]
	v_mfma_f32_16x16x32_bf16 v[8:11], v[184:187], v[216:219], v[8:11]
	s_waitcnt vmcnt(8)
	v_mfma_f32_16x16x32_bf16 v[76:79], v[180:183], v[196:199], v[76:79]
	v_mfma_f32_16x16x32_bf16 v[72:75], v[188:191], v[196:199], v[72:75]
	v_mfma_f32_16x16x32_bf16 v[44:47], v[180:183], v[204:207], v[44:47]
	v_mfma_f32_16x16x32_bf16 v[40:43], v[188:191], v[204:207], v[40:43]
	v_mfma_f32_16x16x32_bf16 v[28:31], v[180:183], v[212:215], v[28:31]
	v_mfma_f32_16x16x32_bf16 v[24:27], v[188:191], v[212:215], v[24:27]
	v_mfma_f32_16x16x32_bf16 v[12:15], v[180:183], v[220:223], v[12:15]
	v_mfma_f32_16x16x32_bf16 v[8:11], v[188:191], v[220:223], v[8:11]
	s_barrier
	s_setprio 0
	s_add_u32 s85, s85, 0x100
	s_addc_u32 s86, s86, 0
	s_add_u32 s44, s44, 0x100
	s_addc_u32 s45, s45, 0
	s_cmp_ge_u32 s87, s84
	s_mov_b32 s46, s87
	s_cbranch_scc1 .Lpeel_done_3
.LBB0_2289:
	ds_read_b128 v[148:151], v159
	ds_read_b128 v[164:167], v159 offset:1024
	ds_read_b128 v[168:171], v159 offset:2048
	ds_read_b128 v[172:175], v159 offset:3072
	ds_read_b128 v[176:179], v160
	ds_read_b128 v[180:183], v160 offset:1024
	ds_read_b128 v[184:187], v160 offset:2048
	ds_read_b128 v[188:191], v160 offset:3072
	s_add_i32 s87, s46, 2
	s_add_u32 s47, s44, 0xfff00080
	s_addc_u32 s48, s45, -1
	s_cmp_eq_u32 s43, s46
	s_cselect_b32 s46, s25, s85
	s_cselect_b32 s49, s37, s48
	s_cselect_b32 s48, s36, s47
	s_cselect_b32 s47, s5, s86
	v_lshl_add_u64 v[152:153], s[44:45], 0, v[142:143]
	s_add_i32 m0, s94, 0xc000
	ds_read_b128 v[192:195], v161
	ds_read_b128 v[196:199], v161 offset:1024
	ds_read_b128 v[200:203], v161 offset:2048
	ds_read_b128 v[204:207], v161 offset:3072
	ds_read_b128 v[208:211], v161 offset:4096
	ds_read_b128 v[212:215], v161 offset:5120
	ds_read_b128 v[216:219], v161 offset:6144
	ds_read_b128 v[220:223], v161 offset:7168
	global_load_lds_dwordx4 v[152:153], off
	v_lshl_add_u64 v[152:153], s[44:45], 0, v[144:145]
	s_add_i32 m0, s94, 0xe000
	s_nop 0
	global_load_lds_dwordx4 v[152:153], off
	s_bitcmp1_b32 s97, 12
	s_cbranch_scc0 .Ldefer_29
	s_waitcnt vmcnt(8)
.Ldefer_29:
	s_waitcnt lgkmcnt(0)
	s_setprio 1
	s_barrier
	v_mfma_f32_16x16x32_bf16 v[112:115], v[148:151], v[192:195], v[112:115]
	v_mfma_f32_16x16x32_bf16 v[116:119], v[168:171], v[192:195], v[116:119]
	v_mfma_f32_16x16x32_bf16 v[100:103], v[148:151], v[200:203], v[100:103]
	v_mfma_f32_16x16x32_bf16 v[96:99], v[168:171], v[200:203], v[96:99]
	v_mfma_f32_16x16x32_bf16 v[84:87], v[148:151], v[208:211], v[84:87]
	v_mfma_f32_16x16x32_bf16 v[80:83], v[168:171], v[208:211], v[80:83]
	v_mfma_f32_16x16x32_bf16 v[52:55], v[148:151], v[216:219], v[52:55]
	v_mfma_f32_16x16x32_bf16 v[48:51], v[168:171], v[216:219], v[48:51]
	v_mfma_f32_16x16x32_bf16 v[112:115], v[164:167], v[196:199], v[112:115]
	v_mfma_f32_16x16x32_bf16 v[116:119], v[172:175], v[196:199], v[116:119]
	v_mfma_f32_16x16x32_bf16 v[100:103], v[164:167], v[204:207], v[100:103]
	v_mfma_f32_16x16x32_bf16 v[96:99], v[172:175], v[204:207], v[96:99]
	v_mfma_f32_16x16x32_bf16 v[84:87], v[164:167], v[212:215], v[84:87]
	v_mfma_f32_16x16x32_bf16 v[80:83], v[172:175], v[212:215], v[80:83]
	v_mfma_f32_16x16x32_bf16 v[52:55], v[164:167], v[220:223], v[52:55]
	v_mfma_f32_16x16x32_bf16 v[48:51], v[172:175], v[220:223], v[48:51]
	s_setprio 0
	s_setprio 1
	v_mfma_f32_16x16x32_bf16 v[124:127], v[176:179], v[192:195], v[124:127]
	v_mfma_f32_16x16x32_bf16 v[120:123], v[184:187], v[192:195], v[120:123]
	v_mfma_f32_16x16x32_bf16 v[108:111], v[176:179], v[200:203], v[108:111]
	v_mfma_f32_16x16x32_bf16 v[104:107], v[184:187], v[200:203], v[104:107]
	v_mfma_f32_16x16x32_bf16 v[92:95], v[176:179], v[208:211], v[92:95]
	v_mfma_f32_16x16x32_bf16 v[88:91], v[184:187], v[208:211], v[88:91]
	v_mfma_f32_16x16x32_bf16 v[68:71], v[176:179], v[216:219], v[68:71]
	v_mfma_f32_16x16x32_bf16 v[64:67], v[184:187], v[216:219], v[64:67]
	s_waitcnt vmcnt(8)
	v_mfma_f32_16x16x32_bf16 v[124:127], v[180:183], v[196:199], v[124:127]
	v_mfma_f32_16x16x32_bf16 v[120:123], v[188:191], v[196:199], v[120:123]
	v_mfma_f32_16x16x32_bf16 v[108:111], v[180:183], v[204:207], v[108:111]
	v_mfma_f32_16x16x32_bf16 v[104:107], v[188:191], v[204:207], v[104:107]
	v_mfma_f32_16x16x32_bf16 v[92:95], v[180:183], v[212:215], v[92:95]
	v_mfma_f32_16x16x32_bf16 v[88:91], v[188:191], v[212:215], v[88:91]
	v_mfma_f32_16x16x32_bf16 v[68:71], v[180:183], v[220:223], v[68:71]
	v_mfma_f32_16x16x32_bf16 v[64:67], v[188:191], v[220:223], v[64:67]
	s_barrier
	s_setprio 0
	s_add_i32 s88, s77, s97
	v_lshl_add_u64 v[152:153], s[46:47], 0, v[132:133]
	s_mov_b32 m0, s88
	ds_read_b128 v[192:195], v161 offset:16384
	ds_read_b128 v[196:199], v161 offset:17408
	ds_read_b128 v[200:203], v161 offset:18432
	ds_read_b128 v[204:207], v161 offset:19456
	ds_read_b128 v[208:211], v161 offset:20480
	ds_read_b128 v[212:215], v161 offset:21504
	ds_read_b128 v[216:219], v161 offset:22528
	ds_read_b128 v[220:223], v161 offset:23552
	global_load_lds_dwordx4 v[152:153], off
	s_add_i32 m0, s88, 0x2000
	s_add_u32 s88, s46, 0x100000
	v_lshl_add_u64 v[224:225], s[46:47], 0, v[136:137]
	s_addc_u32 s89, s47, 0
	s_add_i32 s90, s78, s97
	global_load_lds_dwordx4 v[224:225], off
	v_lshl_add_u64 v[226:227], s[88:89], 0, v[132:133]
	s_mov_b32 m0, s90
	v_lshl_add_u64 v[228:229], s[48:49], 0, v[134:135]
	global_load_lds_dwordx4 v[226:227], off
	v_lshl_add_u64 v[226:227], s[88:89], 0, v[136:137]
	s_add_i32 m0, s90, 0x2000
	s_nop 0
	global_load_lds_dwordx4 v[226:227], off
	v_lshl_add_u64 v[226:227], s[48:49], 0, v[130:131]
	s_mov_b32 m0, s94
	s_nop 0
	global_load_lds_dwordx4 v[226:227], off
	s_mov_b32 m0, s52
	s_nop 0
	global_load_lds_dwordx4 v[228:229], off
	s_bitcmp1_b32 s97, 12
	s_cbranch_scc0 .Ldefer_30
	s_waitcnt vmcnt(8)
.Ldefer_30:
	s_waitcnt lgkmcnt(0)
	s_setprio 1
	s_barrier
	v_mfma_f32_16x16x32_bf16 v[60:63], v[148:151], v[192:195], v[60:63]
	v_mfma_f32_16x16x32_bf16 v[56:59], v[168:171], v[192:195], v[56:59]
	v_mfma_f32_16x16x32_bf16 v[36:39], v[148:151], v[200:203], v[36:39]
	v_mfma_f32_16x16x32_bf16 v[32:35], v[168:171], v[200:203], v[32:35]
	v_mfma_f32_16x16x32_bf16 v[20:23], v[148:151], v[208:211], v[20:23]
	v_mfma_f32_16x16x32_bf16 v[16:19], v[168:171], v[208:211], v[16:19]
	v_mfma_f32_16x16x32_bf16 v[4:7], v[148:151], v[216:219], v[4:7]
	v_mfma_f32_16x16x32_bf16 v[0:3], v[168:171], v[216:219], v[0:3]
	v_mfma_f32_16x16x32_bf16 v[60:63], v[164:167], v[196:199], v[60:63]
	v_mfma_f32_16x16x32_bf16 v[56:59], v[172:175], v[196:199], v[56:59]
	v_mfma_f32_16x16x32_bf16 v[36:39], v[164:167], v[204:207], v[36:39]
	v_mfma_f32_16x16x32_bf16 v[32:35], v[172:175], v[204:207], v[32:35]
	v_mfma_f32_16x16x32_bf16 v[20:23], v[164:167], v[212:215], v[20:23]
	v_mfma_f32_16x16x32_bf16 v[16:19], v[172:175], v[212:215], v[16:19]
	v_mfma_f32_16x16x32_bf16 v[4:7], v[164:167], v[220:223], v[4:7]
	v_mfma_f32_16x16x32_bf16 v[0:3], v[172:175], v[220:223], v[0:3]
	s_setprio 0
	s_setprio 1
	v_mfma_f32_16x16x32_bf16 v[76:79], v[176:179], v[192:195], v[76:79]
	v_mfma_f32_16x16x32_bf16 v[72:75], v[184:187], v[192:195], v[72:75]
	v_mfma_f32_16x16x32_bf16 v[44:47], v[176:179], v[200:203], v[44:47]
	v_mfma_f32_16x16x32_bf16 v[40:43], v[184:187], v[200:203], v[40:43]
	v_mfma_f32_16x16x32_bf16 v[28:31], v[176:179], v[208:211], v[28:31]
	v_mfma_f32_16x16x32_bf16 v[24:27], v[184:187], v[208:211], v[24:27]
	v_mfma_f32_16x16x32_bf16 v[12:15], v[176:179], v[216:219], v[12:15]
	v_mfma_f32_16x16x32_bf16 v[8:11], v[184:187], v[216:219], v[8:11]
	s_waitcnt vmcnt(8)
	v_mfma_f32_16x16x32_bf16 v[76:79], v[180:183], v[196:199], v[76:79]
	v_mfma_f32_16x16x32_bf16 v[72:75], v[188:191], v[196:199], v[72:75]
	v_mfma_f32_16x16x32_bf16 v[44:47], v[180:183], v[204:207], v[44:47]
	v_mfma_f32_16x16x32_bf16 v[40:43], v[188:191], v[204:207], v[40:43]
	v_mfma_f32_16x16x32_bf16 v[28:31], v[180:183], v[212:215], v[28:31]
	v_mfma_f32_16x16x32_bf16 v[24:27], v[188:191], v[212:215], v[24:27]
	v_mfma_f32_16x16x32_bf16 v[12:15], v[180:183], v[220:223], v[12:15]
	v_mfma_f32_16x16x32_bf16 v[8:11], v[188:191], v[220:223], v[8:11]
	s_barrier
	s_setprio 0
	s_add_i32 s88, 0, 0x18000
	v_add_u32_e32 v163, s88, v157
	s_add_i32 s89, 0, 0x1c000
	ds_read_b128 v[148:151], v163
	ds_read_b128 v[164:167], v163 offset:1024
	ds_read_b128 v[168:171], v163 offset:2048
	ds_read_b128 v[172:175], v163 offset:3072
	v_add_u32_e32 v163, s89, v157
	ds_read_b128 v[176:179], v163
	ds_read_b128 v[180:183], v163 offset:1024
	ds_read_b128 v[184:187], v163 offset:2048
	ds_read_b128 v[188:191], v163 offset:3072
	s_add_u32 s48, s48, 0x100000
	s_addc_u32 s49, s49, 0
	s_mov_b32 m0, s53
	v_lshl_add_u64 v[230:231], s[48:49], 0, v[130:131]
	ds_read_b128 v[192:195], v161 offset:32768
	ds_read_b128 v[196:199], v161 offset:33792
	ds_read_b128 v[200:203], v161 offset:34816
	ds_read_b128 v[204:207], v161 offset:35840
	ds_read_b128 v[208:211], v161 offset:36864
	ds_read_b128 v[212:215], v161 offset:37888
	ds_read_b128 v[216:219], v161 offset:38912
	ds_read_b128 v[220:223], v161 offset:39936
	global_load_lds_dwordx4 v[230:231], off
	v_lshl_add_u64 v[230:231], s[48:49], 0, v[134:135]
	s_mov_b32 m0, s54
	s_nop 0
	global_load_lds_dwordx4 v[230:231], off
	s_bitcmp1_b32 s97, 12
	s_cbranch_scc0 .Ldefer_31
	s_waitcnt vmcnt(8)

.Ldefer_32:
	s_waitcnt lgkmcnt(0)
	s_setprio 1
	s_barrier
	v_mfma_f32_16x16x32_bf16 v[60:63], v[148:151], v[192:195], v[60:63]
	v_mfma_f32_16x16x32_bf16 v[56:59], v[168:171], v[192:195], v[56:59]
	v_mfma_f32_16x16x32_bf16 v[36:39], v[148:151], v[200:203], v[36:39]
	v_mfma_f32_16x16x32_bf16 v[32:35], v[168:171], v[200:203], v[32:35]
	v_mfma_f32_16x16x32_bf16 v[20:23], v[148:151], v[208:211], v[20:23]
	v_mfma_f32_16x16x32_bf16 v[16:19], v[168:171], v[208:211], v[16:19]
	v_mfma_f32_16x16x32_bf16 v[4:7], v[148:151], v[216:219], v[4:7]
	v_mfma_f32_16x16x32_bf16 v[0:3], v[168:171], v[216:219], v[0:3]
	v_mfma_f32_16x16x32_bf16 v[60:63], v[164:167], v[196:199], v[60:63]
	v_mfma_f32_16x16x32_bf16 v[56:59], v[172:175], v[196:199], v[56:59]
	v_mfma_f32_16x16x32_bf16 v[36:39], v[164:167], v[204:207], v[36:39]
	v_mfma_f32_16x16x32_bf16 v[32:35], v[172:175], v[204:207], v[32:35]
	v_mfma_f32_16x16x32_bf16 v[20:23], v[164:167], v[212:215], v[20:23]
	v_mfma_f32_16x16x32_bf16 v[16:19], v[172:175], v[212:215], v[16:19]
	v_mfma_f32_16x16x32_bf16 v[4:7], v[164:167], v[220:223], v[4:7]
	v_mfma_f32_16x16x32_bf16 v[0:3], v[172:175], v[220:223], v[0:3]
	s_setprio 0
	s_setprio 1
	v_mfma_f32_16x16x32_bf16 v[76:79], v[176:179], v[192:195], v[76:79]
	v_mfma_f32_16x16x32_bf16 v[72:75], v[184:187], v[192:195], v[72:75]
	v_mfma_f32_16x16x32_bf16 v[44:47], v[176:179], v[200:203], v[44:47]
	v_mfma_f32_16x16x32_bf16 v[40:43], v[184:187], v[200:203], v[40:43]
	v_mfma_f32_16x16x32_bf16 v[28:31], v[176:179], v[208:211], v[28:31]
	v_mfma_f32_16x16x32_bf16 v[24:27], v[184:187], v[208:211], v[24:27]
	v_mfma_f32_16x16x32_bf16 v[12:15], v[176:179], v[216:219], v[12:15]
	v_mfma_f32_16x16x32_bf16 v[8:11], v[184:187], v[216:219], v[8:11]
	s_waitcnt vmcnt(8)
	v_mfma_f32_16x16x32_bf16 v[76:79], v[180:183], v[196:199], v[76:79]
	v_mfma_f32_16x16x32_bf16 v[72:75], v[188:191], v[196:199], v[72:75]
	v_mfma_f32_16x16x32_bf16 v[44:47], v[180:183], v[204:207], v[44:47]
	v_mfma_f32_16x16x32_bf16 v[40:43], v[188:191], v[204:207], v[40:43]
	v_mfma_f32_16x16x32_bf16 v[28:31], v[180:183], v[212:215], v[28:31]
	v_mfma_f32_16x16x32_bf16 v[24:27], v[188:191], v[212:215], v[24:27]
	v_mfma_f32_16x16x32_bf16 v[12:15], v[180:183], v[220:223], v[12:15]
	v_mfma_f32_16x16x32_bf16 v[8:11], v[188:191], v[220:223], v[8:11]
	s_barrier
	s_setprio 0
	s_add_u32 s85, s85, 0x100
	s_addc_u32 s86, s86, 0
	s_add_u32 s44, s44, 0x100
	s_addc_u32 s45, s45, 0
	s_cmp_ge_u32 s87, s84
	s_mov_b32 s46, s87
	s_cbranch_scc0 .LBB0_2289

.LBB0_2452:
	s_cmp_lt_u32 s35, 0x3fffffff
	s_cselect_b64 s[38:39], -1, 0
	s_ashr_i32 s35, s34, 31
	s_and_b64 s[38:39], s[4:5], s[38:39]
	s_lshl_b64 s[4:5], s[34:35], 23
	s_add_u32 s4, s2, s4
	s_addc_u32 s5, s3, s5
	s_add_u32 s4, s4, s36
	s_addc_u32 s5, s5, s37
	s_and_b64 s[48:49], s[38:39], exec
	s_cselect_b32 s35, s5, s47
	s_cselect_b32 s41, s4, s46
	s_ashr_i32 s31, s30, 31
	s_lshl_b64 s[48:49], s[30:31], 23
	v_readlane_b32 s78, v254, 54
	v_readlane_b32 s79, v254, 55
	s_add_u32 s31, s78, s48
	s_addc_u32 s43, s79, s49
	s_add_u32 s36, s31, s36
	s_addc_u32 s37, s43, s37
	s_and_b64 s[48:49], s[38:39], exec
	s_cselect_b32 s31, s37, s45
	s_cselect_b32 s43, s36, s44
	s_add_i32 s75, s76, -2
	s_add_u32 s77, s44, 0x100
	s_addc_u32 s78, s45, 0
	s_add_u32 s44, s46, 0x400080
	s_addc_u32 s45, s47, 0
	s_mov_b32 s46, 0
	ds_read_b128 v[128:131], v228
	ds_read_b128 v[132:135], v228 offset:1024
	ds_read_b128 v[136:139], v228 offset:2048
	ds_read_b128 v[140:143], v228 offset:3072
	ds_read_b128 v[144:147], v229
	ds_read_b128 v[148:151], v229 offset:1024
	ds_read_b128 v[152:155], v229 offset:2048
	ds_read_b128 v[156:159], v229 offset:3072
	s_add_i32 s79, s46, 2
	s_add_u32 s47, s44, 0xffc00080
	s_addc_u32 s48, s45, -1
	s_cmp_eq_u32 s75, s46
	s_cselect_b32 s46, s43, s77
	s_cselect_b32 s49, s35, s48
	s_cselect_b32 s48, s41, s47
	s_cselect_b32 s47, s31, s78
	v_lshl_add_u64 v[208:209], s[44:45], 0, v[202:203]
	s_add_i32 m0, s94, 0xc000
	ds_read_b128 v[160:163], v230
	ds_read_b128 v[164:167], v230 offset:1024
	ds_read_b128 v[168:171], v230 offset:2048
	ds_read_b128 v[172:175], v230 offset:3072
	ds_read_b128 v[176:179], v230 offset:4096
	ds_read_b128 v[180:183], v230 offset:5120
	ds_read_b128 v[184:187], v230 offset:6144
	ds_read_b128 v[188:191], v230 offset:7168
	global_load_lds_dwordx4 v[208:209], off
	v_lshl_add_u64 v[208:209], s[44:45], 0, v[204:205]
	s_add_i32 m0, s94, 0xe000
	s_nop 0
	global_load_lds_dwordx4 v[208:209], off
	s_bitcmp1_b32 s97, 12
	s_cbranch_scc0 .Ldefer_33
	s_waitcnt vmcnt(8)
.Ldefer_33:
	s_waitcnt lgkmcnt(0)
	s_setprio 1
	s_barrier
	v_mfma_f32_16x16x32_bf16 v[112:115], v[128:131], v[160:163], 0
	v_mfma_f32_16x16x32_bf16 v[116:119], v[136:139], v[160:163], 0
	v_mfma_f32_16x16x32_bf16 v[100:103], v[128:131], v[168:171], 0
	v_mfma_f32_16x16x32_bf16 v[96:99], v[136:139], v[168:171], 0
	v_mfma_f32_16x16x32_bf16 v[84:87], v[128:131], v[176:179], 0
	v_mfma_f32_16x16x32_bf16 v[80:83], v[136:139], v[176:179], 0
	v_mfma_f32_16x16x32_bf16 v[52:55], v[128:131], v[184:187], 0
	v_mfma_f32_16x16x32_bf16 v[48:51], v[136:139], v[184:187], 0
	v_mfma_f32_16x16x32_bf16 v[112:115], v[132:135], v[164:167], v[112:115]
	v_mfma_f32_16x16x32_bf16 v[116:119], v[140:143], v[164:167], v[116:119]
	v_mfma_f32_16x16x32_bf16 v[100:103], v[132:135], v[172:175], v[100:103]
	v_mfma_f32_16x16x32_bf16 v[96:99], v[140:143], v[172:175], v[96:99]
	v_mfma_f32_16x16x32_bf16 v[84:87], v[132:135], v[180:183], v[84:87]
	v_mfma_f32_16x16x32_bf16 v[80:83], v[140:143], v[180:183], v[80:83]
	v_mfma_f32_16x16x32_bf16 v[52:55], v[132:135], v[188:191], v[52:55]
	v_mfma_f32_16x16x32_bf16 v[48:51], v[140:143], v[188:191], v[48:51]
	s_setprio 0
	s_setprio 1
	v_mfma_f32_16x16x32_bf16 v[124:127], v[144:147], v[160:163], 0
	v_mfma_f32_16x16x32_bf16 v[120:123], v[152:155], v[160:163], 0
	v_mfma_f32_16x16x32_bf16 v[108:111], v[144:147], v[168:171], 0
	v_mfma_f32_16x16x32_bf16 v[104:107], v[152:155], v[168:171], 0
	v_mfma_f32_16x16x32_bf16 v[92:95], v[144:147], v[176:179], 0
	v_mfma_f32_16x16x32_bf16 v[88:91], v[152:155], v[176:179], 0
	v_mfma_f32_16x16x32_bf16 v[68:71], v[144:147], v[184:187], 0
	v_mfma_f32_16x16x32_bf16 v[64:67], v[152:155], v[184:187], 0
	s_waitcnt vmcnt(8)
	v_mfma_f32_16x16x32_bf16 v[124:127], v[148:151], v[164:167], v[124:127]
	v_mfma_f32_16x16x32_bf16 v[120:123], v[156:159], v[164:167], v[120:123]
	v_mfma_f32_16x16x32_bf16 v[108:111], v[148:151], v[172:175], v[108:111]
	v_mfma_f32_16x16x32_bf16 v[104:107], v[156:159], v[172:175], v[104:107]
	v_mfma_f32_16x16x32_bf16 v[92:95], v[148:151], v[180:183], v[92:95]
	v_mfma_f32_16x16x32_bf16 v[88:91], v[156:159], v[180:183], v[88:91]
	v_mfma_f32_16x16x32_bf16 v[68:71], v[148:151], v[188:191], v[68:71]
	v_mfma_f32_16x16x32_bf16 v[64:67], v[156:159], v[188:191], v[64:67]
	s_barrier
	s_setprio 0
	s_add_i32 s80, s68, s97
	v_lshl_add_u64 v[208:209], s[46:47], 0, v[194:195]
	s_mov_b32 m0, s80
	ds_read_b128 v[160:163], v230 offset:16384
	ds_read_b128 v[164:167], v230 offset:17408
	ds_read_b128 v[168:171], v230 offset:18432
	ds_read_b128 v[172:175], v230 offset:19456
	ds_read_b128 v[176:179], v230 offset:20480
	ds_read_b128 v[180:183], v230 offset:21504
	ds_read_b128 v[184:187], v230 offset:22528
	ds_read_b128 v[188:191], v230 offset:23552
	global_load_lds_dwordx4 v[208:209], off
	s_add_i32 m0, s80, 0x2000
	s_add_u32 s80, s46, 0x400000
	v_lshl_add_u64 v[210:211], s[46:47], 0, v[198:199]
	s_addc_u32 s81, s47, 0
	s_add_i32 s84, s69, s97
	global_load_lds_dwordx4 v[210:211], off
	v_lshl_add_u64 v[212:213], s[80:81], 0, v[194:195]
	s_mov_b32 m0, s84
	v_lshl_add_u64 v[214:215], s[48:49], 0, v[196:197]
	global_load_lds_dwordx4 v[212:213], off
	v_lshl_add_u64 v[212:213], s[80:81], 0, v[198:199]
	s_add_i32 m0, s84, 0x2000
	s_nop 0
	global_load_lds_dwordx4 v[212:213], off
	v_lshl_add_u64 v[212:213], s[48:49], 0, v[192:193]
	s_mov_b32 m0, s94
	s_nop 0
	global_load_lds_dwordx4 v[212:213], off
	s_mov_b32 m0, s51
	s_nop 0
	global_load_lds_dwordx4 v[214:215], off
	s_bitcmp1_b32 s97, 12
	s_cbranch_scc0 .Ldefer_34
	s_waitcnt vmcnt(8)
.Ldefer_34:
	s_waitcnt lgkmcnt(0)
	s_setprio 1
	s_barrier
	v_mfma_f32_16x16x32_bf16 v[60:63], v[128:131], v[160:163], 0
	v_mfma_f32_16x16x32_bf16 v[56:59], v[136:139], v[160:163], 0
	v_mfma_f32_16x16x32_bf16 v[36:39], v[128:131], v[168:171], 0
	v_mfma_f32_16x16x32_bf16 v[32:35], v[136:139], v[168:171], 0
	v_mfma_f32_16x16x32_bf16 v[20:23], v[128:131], v[176:179], 0
	v_mfma_f32_16x16x32_bf16 v[16:19], v[136:139], v[176:179], 0
	v_mfma_f32_16x16x32_bf16 v[4:7], v[128:131], v[184:187], 0
	v_mfma_f32_16x16x32_bf16 v[0:3], v[136:139], v[184:187], 0
	v_mfma_f32_16x16x32_bf16 v[60:63], v[132:135], v[164:167], v[60:63]
	v_mfma_f32_16x16x32_bf16 v[56:59], v[140:143], v[164:167], v[56:59]
	v_mfma_f32_16x16x32_bf16 v[36:39], v[132:135], v[172:175], v[36:39]
	v_mfma_f32_16x16x32_bf16 v[32:35], v[140:143], v[172:175], v[32:35]
	v_mfma_f32_16x16x32_bf16 v[20:23], v[132:135], v[180:183], v[20:23]
	v_mfma_f32_16x16x32_bf16 v[16:19], v[140:143], v[180:183], v[16:19]
	v_mfma_f32_16x16x32_bf16 v[4:7], v[132:135], v[188:191], v[4:7]
	v_mfma_f32_16x16x32_bf16 v[0:3], v[140:143], v[188:191], v[0:3]
	s_setprio 0
	s_setprio 1
	v_mfma_f32_16x16x32_bf16 v[76:79], v[144:147], v[160:163], 0
	v_mfma_f32_16x16x32_bf16 v[72:75], v[152:155], v[160:163], 0
	v_mfma_f32_16x16x32_bf16 v[44:47], v[144:147], v[168:171], 0
	v_mfma_f32_16x16x32_bf16 v[40:43], v[152:155], v[168:171], 0
	v_mfma_f32_16x16x32_bf16 v[28:31], v[144:147], v[176:179], 0
	v_mfma_f32_16x16x32_bf16 v[24:27], v[152:155], v[176:179], 0
	v_mfma_f32_16x16x32_bf16 v[12:15], v[144:147], v[184:187], 0
	v_mfma_f32_16x16x32_bf16 v[8:11], v[152:155], v[184:187], 0
	s_waitcnt vmcnt(8)
	v_mfma_f32_16x16x32_bf16 v[76:79], v[148:151], v[164:167], v[76:79]
	v_mfma_f32_16x16x32_bf16 v[72:75], v[156:159], v[164:167], v[72:75]
	v_mfma_f32_16x16x32_bf16 v[44:47], v[148:151], v[172:175], v[44:47]
	v_mfma_f32_16x16x32_bf16 v[40:43], v[156:159], v[172:175], v[40:43]
	v_mfma_f32_16x16x32_bf16 v[28:31], v[148:151], v[180:183], v[28:31]
	v_mfma_f32_16x16x32_bf16 v[24:27], v[156:159], v[180:183], v[24:27]
	v_mfma_f32_16x16x32_bf16 v[12:15], v[148:151], v[188:191], v[12:15]
	v_mfma_f32_16x16x32_bf16 v[8:11], v[156:159], v[188:191], v[8:11]
	s_barrier
	s_setprio 0
	s_add_i32 s80, 0, 0x18000
	s_add_i32 s81, 0, 0x1c000
	v_add_u32_e32 v140, s80, v226
	v_add_u32_e32 v156, s81, v226
	ds_read_b128 v[128:131], v140
	ds_read_b128 v[132:135], v140 offset:1024
	ds_read_b128 v[136:139], v140 offset:2048
	ds_read_b128 v[140:143], v140 offset:3072
	ds_read_b128 v[144:147], v156
	ds_read_b128 v[148:151], v156 offset:1024
	ds_read_b128 v[152:155], v156 offset:2048
	ds_read_b128 v[156:159], v156 offset:3072
	s_add_u32 s48, s48, 0x400000
	s_addc_u32 s49, s49, 0
	s_mov_b32 m0, s52
	v_lshl_add_u64 v[216:217], s[48:49], 0, v[192:193]
	ds_read_b128 v[160:163], v230 offset:32768
	ds_read_b128 v[164:167], v230 offset:33792
	ds_read_b128 v[168:171], v230 offset:34816
	ds_read_b128 v[172:175], v230 offset:35840
	ds_read_b128 v[176:179], v230 offset:36864
	ds_read_b128 v[180:183], v230 offset:37888
	ds_read_b128 v[184:187], v230 offset:38912
	ds_read_b128 v[188:191], v230 offset:39936
	global_load_lds_dwordx4 v[216:217], off
	v_lshl_add_u64 v[216:217], s[48:49], 0, v[196:197]
	s_mov_b32 m0, s53
	s_nop 0
	global_load_lds_dwordx4 v[216:217], off
	s_bitcmp1_b32 s97, 12
	s_cbranch_scc0 .Ldefer_35
	s_waitcnt vmcnt(8)
.Ldefer_35:
	s_waitcnt lgkmcnt(0)
	s_setprio 1
	s_barrier
	v_mfma_f32_16x16x32_bf16 v[112:115], v[128:131], v[160:163], v[112:115]
	v_mfma_f32_16x16x32_bf16 v[116:119], v[136:139], v[160:163], v[116:119]
	v_mfma_f32_16x16x32_bf16 v[100:103], v[128:131], v[168:171], v[100:103]
	v_mfma_f32_16x16x32_bf16 v[96:99], v[136:139], v[168:171], v[96:99]
	v_mfma_f32_16x16x32_bf16 v[84:87], v[128:131], v[176:179], v[84:87]
	v_mfma_f32_16x16x32_bf16 v[80:83], v[136:139], v[176:179], v[80:83]
	v_mfma_f32_16x16x32_bf16 v[52:55], v[128:131], v[184:187], v[52:55]
	v_mfma_f32_16x16x32_bf16 v[48:51], v[136:139], v[184:187], v[48:51]
	v_mfma_f32_16x16x32_bf16 v[112:115], v[132:135], v[164:167], v[112:115]
	v_mfma_f32_16x16x32_bf16 v[116:119], v[140:143], v[164:167], v[116:119]
	v_mfma_f32_16x16x32_bf16 v[100:103], v[132:135], v[172:175], v[100:103]
	v_mfma_f32_16x16x32_bf16 v[96:99], v[140:143], v[172:175], v[96:99]
	v_mfma_f32_16x16x32_bf16 v[84:87], v[132:135], v[180:183], v[84:87]
	v_mfma_f32_16x16x32_bf16 v[80:83], v[140:143], v[180:183], v[80:83]
	v_mfma_f32_16x16x32_bf16 v[52:55], v[132:135], v[188:191], v[52:55]
	v_mfma_f32_16x16x32_bf16 v[48:51], v[140:143], v[188:191], v[48:51]
	s_setprio 0
	s_setprio 1
	v_mfma_f32_16x16x32_bf16 v[124:127], v[144:147], v[160:163], v[124:127]
	v_mfma_f32_16x16x32_bf16 v[120:123], v[152:155], v[160:163], v[120:123]
	v_mfma_f32_16x16x32_bf16 v[108:111], v[144:147], v[168:171], v[108:111]
	v_mfma_f32_16x16x32_bf16 v[104:107], v[152:155], v[168:171], v[104:107]
	v_mfma_f32_16x16x32_bf16 v[92:95], v[144:147], v[176:179], v[92:95]
	v_mfma_f32_16x16x32_bf16 v[88:91], v[152:155], v[176:179], v[88:91]
	v_mfma_f32_16x16x32_bf16 v[68:71], v[144:147], v[184:187], v[68:71]
	v_mfma_f32_16x16x32_bf16 v[64:67], v[152:155], v[184:187], v[64:67]
	s_waitcnt vmcnt(8)
	v_mfma_f32_16x16x32_bf16 v[124:127], v[148:151], v[164:167], v[124:127]
	v_mfma_f32_16x16x32_bf16 v[120:123], v[156:159], v[164:167], v[120:123]
	v_mfma_f32_16x16x32_bf16 v[108:111], v[148:151], v[172:175], v[108:111]
	v_mfma_f32_16x16x32_bf16 v[104:107], v[156:159], v[172:175], v[104:107]
	v_mfma_f32_16x16x32_bf16 v[92:95], v[148:151], v[180:183], v[92:95]
	v_mfma_f32_16x16x32_bf16 v[88:91], v[156:159], v[180:183], v[88:91]
	v_mfma_f32_16x16x32_bf16 v[68:71], v[148:151], v[188:191], v[68:71]
	v_mfma_f32_16x16x32_bf16 v[64:67], v[156:159], v[188:191], v[64:67]
	s_barrier
	s_setprio 0
	s_add_i32 s48, s80, s97
	v_lshl_add_u64 v[208:209], v[208:209], 0, s[12:13]
	s_mov_b32 m0, s48
	ds_read_b128 v[160:163], v230 offset:49152
	ds_read_b128 v[164:167], v230 offset:50176
	ds_read_b128 v[168:171], v230 offset:51200
	ds_read_b128 v[172:175], v230 offset:52224
	ds_read_b128 v[176:179], v230 offset:53248
	ds_read_b128 v[180:183], v230 offset:54272
	ds_read_b128 v[184:187], v230 offset:55296
	ds_read_b128 v[188:191], v230 offset:56320
	global_load_lds_dwordx4 v[208:209], off
	s_add_i32 m0, s48, 0x2000
	s_add_u32 s46, s46, 0x400080
	v_lshl_add_u64 v[208:209], v[210:211], 0, s[12:13]
	s_addc_u32 s47, s47, 0
	s_add_i32 s48, s81, s97
	global_load_lds_dwordx4 v[208:209], off
	v_lshl_add_u64 v[208:209], s[46:47], 0, v[194:195]
	s_mov_b32 m0, s48
	s_nop 0
	global_load_lds_dwordx4 v[208:209], off
	v_lshl_add_u64 v[208:209], s[46:47], 0, v[198:199]
	s_add_i32 m0, s48, 0x2000
	s_nop 0
	global_load_lds_dwordx4 v[208:209], off
	v_lshl_add_u64 v[208:209], v[212:213], 0, s[12:13]
	s_mov_b32 m0, s54
	s_nop 0
	global_load_lds_dwordx4 v[208:209], off
	v_lshl_add_u64 v[208:209], v[214:215], 0, s[12:13]
	s_mov_b32 m0, s55
	s_nop 0
	global_load_lds_dwordx4 v[208:209], off
	s_bitcmp1_b32 s97, 12
	s_cbranch_scc0 .Ldefer_36
	s_waitcnt vmcnt(8)
.Ldefer_36:
	s_waitcnt lgkmcnt(0)
	s_setprio 1
	s_barrier
	v_mfma_f32_16x16x32_bf16 v[60:63], v[128:131], v[160:163], v[60:63]
	v_mfma_f32_16x16x32_bf16 v[56:59], v[136:139], v[160:163], v[56:59]
	v_mfma_f32_16x16x32_bf16 v[36:39], v[128:131], v[168:171], v[36:39]
	v_mfma_f32_16x16x32_bf16 v[32:35], v[136:139], v[168:171], v[32:35]
	v_mfma_f32_16x16x32_bf16 v[20:23], v[128:131], v[176:179], v[20:23]
	v_mfma_f32_16x16x32_bf16 v[16:19], v[136:139], v[176:179], v[16:19]
	v_mfma_f32_16x16x32_bf16 v[4:7], v[128:131], v[184:187], v[4:7]
	v_mfma_f32_16x16x32_bf16 v[0:3], v[136:139], v[184:187], v[0:3]
	v_mfma_f32_16x16x32_bf16 v[60:63], v[132:135], v[164:167], v[60:63]
	v_mfma_f32_16x16x32_bf16 v[56:59], v[140:143], v[164:167], v[56:59]
	v_mfma_f32_16x16x32_bf16 v[36:39], v[132:135], v[172:175], v[36:39]
	v_mfma_f32_16x16x32_bf16 v[32:35], v[140:143], v[172:175], v[32:35]
	v_mfma_f32_16x16x32_bf16 v[20:23], v[132:135], v[180:183], v[20:23]
	v_mfma_f32_16x16x32_bf16 v[16:19], v[140:143], v[180:183], v[16:19]
	v_mfma_f32_16x16x32_bf16 v[4:7], v[132:135], v[188:191], v[4:7]
	v_mfma_f32_16x16x32_bf16 v[0:3], v[140:143], v[188:191], v[0:3]
	s_setprio 0
	s_setprio 1
	v_mfma_f32_16x16x32_bf16 v[76:79], v[144:147], v[160:163], v[76:79]
	v_mfma_f32_16x16x32_bf16 v[72:75], v[152:155], v[160:163], v[72:75]
	v_mfma_f32_16x16x32_bf16 v[44:47], v[144:147], v[168:171], v[44:47]
	v_mfma_f32_16x16x32_bf16 v[40:43], v[152:155], v[168:171], v[40:43]
	v_mfma_f32_16x16x32_bf16 v[28:31], v[144:147], v[176:179], v[28:31]
	v_mfma_f32_16x16x32_bf16 v[24:27], v[152:155], v[176:179], v[24:27]
	v_mfma_f32_16x16x32_bf16 v[12:15], v[144:147], v[184:187], v[12:15]
	v_mfma_f32_16x16x32_bf16 v[8:11], v[152:155], v[184:187], v[8:11]
	s_waitcnt vmcnt(8)
	v_mfma_f32_16x16x32_bf16 v[76:79], v[148:151], v[164:167], v[76:79]
	v_mfma_f32_16x16x32_bf16 v[72:75], v[156:159], v[164:167], v[72:75]
	v_mfma_f32_16x16x32_bf16 v[44:47], v[148:151], v[172:175], v[44:47]
	v_mfma_f32_16x16x32_bf16 v[40:43], v[156:159], v[172:175], v[40:43]
	v_mfma_f32_16x16x32_bf16 v[28:31], v[148:151], v[180:183], v[28:31]
	v_mfma_f32_16x16x32_bf16 v[24:27], v[156:159], v[180:183], v[24:27]
	v_mfma_f32_16x16x32_bf16 v[12:15], v[148:151], v[188:191], v[12:15]
	v_mfma_f32_16x16x32_bf16 v[8:11], v[156:159], v[188:191], v[8:11]
	s_barrier
	s_setprio 0
	s_add_u32 s77, s77, 0x100
	s_addc_u32 s78, s78, 0
	s_add_u32 s44, s44, 0x100
	s_addc_u32 s45, s45, 0
	s_cmp_ge_u32 s79, s76
	s_mov_b32 s46, s79
	s_cbranch_scc1 .Lpeel_done_4
.LBB0_2453:
	ds_read_b128 v[128:131], v228
	ds_read_b128 v[132:135], v228 offset:1024
	ds_read_b128 v[136:139], v228 offset:2048
	ds_read_b128 v[140:143], v228 offset:3072
	ds_read_b128 v[144:147], v229
	ds_read_b128 v[148:151], v229 offset:1024
	ds_read_b128 v[152:155], v229 offset:2048
	ds_read_b128 v[156:159], v229 offset:3072
	s_add_i32 s79, s46, 2
	s_add_u32 s47, s44, 0xffc00080
	s_addc_u32 s48, s45, -1
	s_cmp_eq_u32 s75, s46
	s_cselect_b32 s46, s43, s77
	s_cselect_b32 s49, s35, s48
	s_cselect_b32 s48, s41, s47
	s_cselect_b32 s47, s31, s78
	v_lshl_add_u64 v[208:209], s[44:45], 0, v[202:203]
	s_add_i32 m0, s94, 0xc000
	ds_read_b128 v[160:163], v230
	ds_read_b128 v[164:167], v230 offset:1024
	ds_read_b128 v[168:171], v230 offset:2048
	ds_read_b128 v[172:175], v230 offset:3072
	ds_read_b128 v[176:179], v230 offset:4096
	ds_read_b128 v[180:183], v230 offset:5120
	ds_read_b128 v[184:187], v230 offset:6144
	ds_read_b128 v[188:191], v230 offset:7168
	global_load_lds_dwordx4 v[208:209], off
	v_lshl_add_u64 v[208:209], s[44:45], 0, v[204:205]
	s_add_i32 m0, s94, 0xe000
	s_nop 0
	global_load_lds_dwordx4 v[208:209], off
	s_bitcmp1_b32 s97, 12
	s_cbranch_scc0 .Ldefer_37
	s_waitcnt vmcnt(8)
.Ldefer_37:
	s_waitcnt lgkmcnt(0)
	s_setprio 1
	s_barrier
	v_mfma_f32_16x16x32_bf16 v[112:115], v[128:131], v[160:163], v[112:115]
	v_mfma_f32_16x16x32_bf16 v[116:119], v[136:139], v[160:163], v[116:119]
	v_mfma_f32_16x16x32_bf16 v[100:103], v[128:131], v[168:171], v[100:103]
	v_mfma_f32_16x16x32_bf16 v[96:99], v[136:139], v[168:171], v[96:99]
	v_mfma_f32_16x16x32_bf16 v[84:87], v[128:131], v[176:179], v[84:87]
	v_mfma_f32_16x16x32_bf16 v[80:83], v[136:139], v[176:179], v[80:83]
	v_mfma_f32_16x16x32_bf16 v[52:55], v[128:131], v[184:187], v[52:55]
	v_mfma_f32_16x16x32_bf16 v[48:51], v[136:139], v[184:187], v[48:51]
	v_mfma_f32_16x16x32_bf16 v[112:115], v[132:135], v[164:167], v[112:115]
	v_mfma_f32_16x16x32_bf16 v[116:119], v[140:143], v[164:167], v[116:119]
	v_mfma_f32_16x16x32_bf16 v[100:103], v[132:135], v[172:175], v[100:103]
	v_mfma_f32_16x16x32_bf16 v[96:99], v[140:143], v[172:175], v[96:99]
	v_mfma_f32_16x16x32_bf16 v[84:87], v[132:135], v[180:183], v[84:87]
	v_mfma_f32_16x16x32_bf16 v[80:83], v[140:143], v[180:183], v[80:83]
	v_mfma_f32_16x16x32_bf16 v[52:55], v[132:135], v[188:191], v[52:55]
	v_mfma_f32_16x16x32_bf16 v[48:51], v[140:143], v[188:191], v[48:51]
	s_setprio 0
	s_setprio 1
	v_mfma_f32_16x16x32_bf16 v[124:127], v[144:147], v[160:163], v[124:127]
	v_mfma_f32_16x16x32_bf16 v[120:123], v[152:155], v[160:163], v[120:123]
	v_mfma_f32_16x16x32_bf16 v[108:111], v[144:147], v[168:171], v[108:111]
	v_mfma_f32_16x16x32_bf16 v[104:107], v[152:155], v[168:171], v[104:107]
	v_mfma_f32_16x16x32_bf16 v[92:95], v[144:147], v[176:179], v[92:95]
	v_mfma_f32_16x16x32_bf16 v[88:91], v[152:155], v[176:179], v[88:91]
	v_mfma_f32_16x16x32_bf16 v[68:71], v[144:147], v[184:187], v[68:71]
	v_mfma_f32_16x16x32_bf16 v[64:67], v[152:155], v[184:187], v[64:67]
	s_waitcnt vmcnt(8)
	v_mfma_f32_16x16x32_bf16 v[124:127], v[148:151], v[164:167], v[124:127]
	v_mfma_f32_16x16x32_bf16 v[120:123], v[156:159], v[164:167], v[120:123]
	v_mfma_f32_16x16x32_bf16 v[108:111], v[148:151], v[172:175], v[108:111]
	v_mfma_f32_16x16x32_bf16 v[104:107], v[156:159], v[172:175], v[104:107]
	v_mfma_f32_16x16x32_bf16 v[92:95], v[148:151], v[180:183], v[92:95]
	v_mfma_f32_16x16x32_bf16 v[88:91], v[156:159], v[180:183], v[88:91]
	v_mfma_f32_16x16x32_bf16 v[68:71], v[148:151], v[188:191], v[68:71]
	v_mfma_f32_16x16x32_bf16 v[64:67], v[156:159], v[188:191], v[64:67]
	s_barrier
	s_setprio 0
	s_add_i32 s80, s68, s97
	v_lshl_add_u64 v[208:209], s[46:47], 0, v[194:195]
	s_mov_b32 m0, s80
	ds_read_b128 v[160:163], v230 offset:16384
	ds_read_b128 v[164:167], v230 offset:17408
	ds_read_b128 v[168:171], v230 offset:18432
	ds_read_b128 v[172:175], v230 offset:19456
	ds_read_b128 v[176:179], v230 offset:20480
	ds_read_b128 v[180:183], v230 offset:21504
	ds_read_b128 v[184:187], v230 offset:22528
	ds_read_b128 v[188:191], v230 offset:23552
	global_load_lds_dwordx4 v[208:209], off
	s_add_i32 m0, s80, 0x2000
	s_add_u32 s80, s46, 0x400000
	v_lshl_add_u64 v[210:211], s[46:47], 0, v[198:199]
	s_addc_u32 s81, s47, 0
	s_add_i32 s84, s69, s97
	global_load_lds_dwordx4 v[210:211], off
	v_lshl_add_u64 v[212:213], s[80:81], 0, v[194:195]
	s_mov_b32 m0, s84
	v_lshl_add_u64 v[214:215], s[48:49], 0, v[196:197]
	global_load_lds_dwordx4 v[212:213], off
	v_lshl_add_u64 v[212:213], s[80:81], 0, v[198:199]
	s_add_i32 m0, s84, 0x2000
	s_nop 0
	global_load_lds_dwordx4 v[212:213], off
	v_lshl_add_u64 v[212:213], s[48:49], 0, v[192:193]
	s_mov_b32 m0, s94
	s_nop 0
	global_load_lds_dwordx4 v[212:213], off
	s_mov_b32 m0, s51
	s_nop 0
	global_load_lds_dwordx4 v[214:215], off
	s_bitcmp1_b32 s97, 12
	s_cbranch_scc0 .Ldefer_38
	s_waitcnt vmcnt(8)
.Ldefer_38:
	s_waitcnt lgkmcnt(0)
	s_setprio 1
	s_barrier
	v_mfma_f32_16x16x32_bf16 v[60:63], v[128:131], v[160:163], v[60:63]
	v_mfma_f32_16x16x32_bf16 v[56:59], v[136:139], v[160:163], v[56:59]
	v_mfma_f32_16x16x32_bf16 v[36:39], v[128:131], v[168:171], v[36:39]
	v_mfma_f32_16x16x32_bf16 v[32:35], v[136:139], v[168:171], v[32:35]
	v_mfma_f32_16x16x32_bf16 v[20:23], v[128:131], v[176:179], v[20:23]
	v_mfma_f32_16x16x32_bf16 v[16:19], v[136:139], v[176:179], v[16:19]
	v_mfma_f32_16x16x32_bf16 v[4:7], v[128:131], v[184:187], v[4:7]
	v_mfma_f32_16x16x32_bf16 v[0:3], v[136:139], v[184:187], v[0:3]
	v_mfma_f32_16x16x32_bf16 v[60:63], v[132:135], v[164:167], v[60:63]
	v_mfma_f32_16x16x32_bf16 v[56:59], v[140:143], v[164:167], v[56:59]
	v_mfma_f32_16x16x32_bf16 v[36:39], v[132:135], v[172:175], v[36:39]
	v_mfma_f32_16x16x32_bf16 v[32:35], v[140:143], v[172:175], v[32:35]
	v_mfma_f32_16x16x32_bf16 v[20:23], v[132:135], v[180:183], v[20:23]
	v_mfma_f32_16x16x32_bf16 v[16:19], v[140:143], v[180:183], v[16:19]
	v_mfma_f32_16x16x32_bf16 v[4:7], v[132:135], v[188:191], v[4:7]
	v_mfma_f32_16x16x32_bf16 v[0:3], v[140:143], v[188:191], v[0:3]
	s_setprio 0
	s_setprio 1
	v_mfma_f32_16x16x32_bf16 v[76:79], v[144:147], v[160:163], v[76:79]
	v_mfma_f32_16x16x32_bf16 v[72:75], v[152:155], v[160:163], v[72:75]
	v_mfma_f32_16x16x32_bf16 v[44:47], v[144:147], v[168:171], v[44:47]
	v_mfma_f32_16x16x32_bf16 v[40:43], v[152:155], v[168:171], v[40:43]
	v_mfma_f32_16x16x32_bf16 v[28:31], v[144:147], v[176:179], v[28:31]
	v_mfma_f32_16x16x32_bf16 v[24:27], v[152:155], v[176:179], v[24:27]
	v_mfma_f32_16x16x32_bf16 v[12:15], v[144:147], v[184:187], v[12:15]
	v_mfma_f32_16x16x32_bf16 v[8:11], v[152:155], v[184:187], v[8:11]
	s_waitcnt vmcnt(8)
	v_mfma_f32_16x16x32_bf16 v[76:79], v[148:151], v[164:167], v[76:79]
	v_mfma_f32_16x16x32_bf16 v[72:75], v[156:159], v[164:167], v[72:75]
	v_mfma_f32_16x16x32_bf16 v[44:47], v[148:151], v[172:175], v[44:47]
	v_mfma_f32_16x16x32_bf16 v[40:43], v[156:159], v[172:175], v[40:43]
	v_mfma_f32_16x16x32_bf16 v[28:31], v[148:151], v[180:183], v[28:31]
	v_mfma_f32_16x16x32_bf16 v[24:27], v[156:159], v[180:183], v[24:27]
	v_mfma_f32_16x16x32_bf16 v[12:15], v[148:151], v[188:191], v[12:15]
	v_mfma_f32_16x16x32_bf16 v[8:11], v[156:159], v[188:191], v[8:11]
	s_barrier
	s_setprio 0
	s_add_i32 s80, 0, 0x18000
	s_add_i32 s81, 0, 0x1c000
	v_add_u32_e32 v140, s80, v226
	v_add_u32_e32 v156, s81, v226
	ds_read_b128 v[128:131], v140
	ds_read_b128 v[132:135], v140 offset:1024
	ds_read_b128 v[136:139], v140 offset:2048
	ds_read_b128 v[140:143], v140 offset:3072
	ds_read_b128 v[144:147], v156
	ds_read_b128 v[148:151], v156 offset:1024
	ds_read_b128 v[152:155], v156 offset:2048
	ds_read_b128 v[156:159], v156 offset:3072
	s_add_u32 s48, s48, 0x400000
	s_addc_u32 s49, s49, 0
	s_mov_b32 m0, s52
	v_lshl_add_u64 v[216:217], s[48:49], 0, v[192:193]
	ds_read_b128 v[160:163], v230 offset:32768
	ds_read_b128 v[164:167], v230 offset:33792
	ds_read_b128 v[168:171], v230 offset:34816
	ds_read_b128 v[172:175], v230 offset:35840
	ds_read_b128 v[176:179], v230 offset:36864
	ds_read_b128 v[180:183], v230 offset:37888
	ds_read_b128 v[184:187], v230 offset:38912
	ds_read_b128 v[188:191], v230 offset:39936
	global_load_lds_dwordx4 v[216:217], off
	v_lshl_add_u64 v[216:217], s[48:49], 0, v[196:197]
	s_mov_b32 m0, s53
	s_nop 0
	global_load_lds_dwordx4 v[216:217], off
	s_bitcmp1_b32 s97, 12
	s_cbranch_scc0 .Ldefer_39
	s_waitcnt vmcnt(8)

.Ldefer_40:
	s_waitcnt lgkmcnt(0)
	s_setprio 1
	s_barrier
	v_mfma_f32_16x16x32_bf16 v[60:63], v[128:131], v[160:163], v[60:63]
	v_mfma_f32_16x16x32_bf16 v[56:59], v[136:139], v[160:163], v[56:59]
	v_mfma_f32_16x16x32_bf16 v[36:39], v[128:131], v[168:171], v[36:39]
	v_mfma_f32_16x16x32_bf16 v[32:35], v[136:139], v[168:171], v[32:35]
	v_mfma_f32_16x16x32_bf16 v[20:23], v[128:131], v[176:179], v[20:23]
	v_mfma_f32_16x16x32_bf16 v[16:19], v[136:139], v[176:179], v[16:19]
	v_mfma_f32_16x16x32_bf16 v[4:7], v[128:131], v[184:187], v[4:7]
	v_mfma_f32_16x16x32_bf16 v[0:3], v[136:139], v[184:187], v[0:3]
	v_mfma_f32_16x16x32_bf16 v[60:63], v[132:135], v[164:167], v[60:63]
	v_mfma_f32_16x16x32_bf16 v[56:59], v[140:143], v[164:167], v[56:59]
	v_mfma_f32_16x16x32_bf16 v[36:39], v[132:135], v[172:175], v[36:39]
	v_mfma_f32_16x16x32_bf16 v[32:35], v[140:143], v[172:175], v[32:35]
	v_mfma_f32_16x16x32_bf16 v[20:23], v[132:135], v[180:183], v[20:23]
	v_mfma_f32_16x16x32_bf16 v[16:19], v[140:143], v[180:183], v[16:19]
	v_mfma_f32_16x16x32_bf16 v[4:7], v[132:135], v[188:191], v[4:7]
	v_mfma_f32_16x16x32_bf16 v[0:3], v[140:143], v[188:191], v[0:3]
	s_setprio 0
	s_setprio 1
	v_mfma_f32_16x16x32_bf16 v[76:79], v[144:147], v[160:163], v[76:79]
	v_mfma_f32_16x16x32_bf16 v[72:75], v[152:155], v[160:163], v[72:75]
	v_mfma_f32_16x16x32_bf16 v[44:47], v[144:147], v[168:171], v[44:47]
	v_mfma_f32_16x16x32_bf16 v[40:43], v[152:155], v[168:171], v[40:43]
	v_mfma_f32_16x16x32_bf16 v[28:31], v[144:147], v[176:179], v[28:31]
	v_mfma_f32_16x16x32_bf16 v[24:27], v[152:155], v[176:179], v[24:27]
	v_mfma_f32_16x16x32_bf16 v[12:15], v[144:147], v[184:187], v[12:15]
	v_mfma_f32_16x16x32_bf16 v[8:11], v[152:155], v[184:187], v[8:11]
	s_waitcnt vmcnt(8)
	v_mfma_f32_16x16x32_bf16 v[76:79], v[148:151], v[164:167], v[76:79]
	v_mfma_f32_16x16x32_bf16 v[72:75], v[156:159], v[164:167], v[72:75]
	v_mfma_f32_16x16x32_bf16 v[44:47], v[148:151], v[172:175], v[44:47]
	v_mfma_f32_16x16x32_bf16 v[40:43], v[156:159], v[172:175], v[40:43]
	v_mfma_f32_16x16x32_bf16 v[28:31], v[148:151], v[180:183], v[28:31]
	v_mfma_f32_16x16x32_bf16 v[24:27], v[156:159], v[180:183], v[24:27]
	v_mfma_f32_16x16x32_bf16 v[12:15], v[148:151], v[188:191], v[12:15]
	v_mfma_f32_16x16x32_bf16 v[8:11], v[156:159], v[188:191], v[8:11]
	s_barrier
	s_setprio 0
	s_add_u32 s77, s77, 0x100
	s_addc_u32 s78, s78, 0
	s_add_u32 s44, s44, 0x100
	s_addc_u32 s45, s45, 0
	s_cmp_ge_u32 s79, s76
	s_mov_b32 s46, s79
	s_cbranch_scc0 .LBB0_2453
